# mlstm_out: n-state (snp) load issued with the hoisted gate loads instead of a drained round trip after the batch
# baseline (speedup 1.0000x reference)
.LBB0_1153:
	s_mov_b64 s[10:11], s[62:63]
	s_load_dwordx2 s[24:25], s[10:11], 0xc0
	s_load_dwordx2 s[30:31], s[10:11], 0x38
	s_load_dwordx2 s[34:35], s[10:11], 0x28
	s_load_dwordx2 s[42:43], s[10:11], 0x30
	v_mov_b32_e32 v64, v208
	s_and_b32 s13, s27, 0xfffff800
	s_and_b32 s6, s26, 0x780
	s_lshr_b32 s7, s28, 4
	v_ashrrev_i32_e32 v159, 6, v64
	s_bfe_u32 s12, s28, 0x20004
	s_or_b32 s5, s13, s6
	v_lshlrev_b32_e32 v95, 4, v159
	s_lshl_b32 s29, s12, 7
	s_bfe_u32 s96, s7, 0x10001
	v_and_b32_e32 v50, 63, v64
	v_add_u32_e32 v72, s5, v95
	s_or_b32 s7, s96, 6
	v_mov_b32_e32 v6, s29
	v_lshlrev_b32_e32 v160, 1, v50
	s_movk_i32 s0, 0xfe
	v_ashrrev_i32_e32 v73, 31, v72
	s_or_b32 s10, s96, 8
	v_mov_b32_e32 v166, s7
	v_bitop3_b32 v8, v160, s0, v6 bitop3:0xc8
	v_lshlrev_b32_e32 v6, 8, v72
	v_alignbit_b32 v52, v73, v72, 8
	v_mov_b32_e32 v5, v167
	v_mov_b32_e32 v4, s10
	v_and_b32_e32 v9, 0xf000, v6
	v_mad_u64_u32 v[6:7], s[10:11], v52, 49, v[166:167]
	v_mad_u64_u32 v[4:5], s[10:11], v52, 49, v[4:5]
	v_mad_u32_u24 v7, v73, 49, v7
	s_mov_b64 s[2:3], 0x74c2800
	v_mad_u32_u24 v5, v73, 49, v5
	v_lshlrev_b64 v[6:7], 17, v[6:7]
	v_lshlrev_b32_e32 v166, 1, v8
	v_lshlrev_b64 v[4:5], 17, v[4:5]
	v_mov_b32_e32 v19, v167
	v_lshlrev_b32_e32 v18, 1, v9
	v_lshlrev_b32_e32 v51, 3, v64
	v_or_b32_e32 v48, s29, v160
	s_lshl_b64 s[10:11], s[18:19], 2
	v_mov_b64_e32 v[30:31], s[96:97]
	s_waitcnt lgkmcnt(0)
	v_mov_b32_e32 v74, s24
	v_mov_b32_e32 v75, s25
	v_mov_b32_e32 v76, s30
	v_mov_b32_e32 v77, s31
	v_mov_b32_e32 v0, s34
	v_mov_b32_e32 v1, s35
	v_mov_b32_e32 v2, s42
	v_mov_b32_e32 v3, s43
	v_lshl_add_u64 v[20:21], v[74:75], 0, s[2:3]
	v_cmp_gt_i32_e32 vcc, 0x80, v208
	s_and_saveexec_b64 s[30:31], vcc
	v_add_u32_e32 v224, s5, v208
	v_ashrrev_i32_e32 v225, 31, v224
	v_lshlrev_b64 v[224:225], 5, v[224:225]
	v_lshl_add_u64 v[224:225], v[74:75], 0, v[224:225]
	s_lshl_b32 s24, s12, 2
	s_mov_b32 s25, 0
	v_lshl_add_u64 v[224:225], v[224:225], 0, s[24:25]
	s_mov_b64 s[34:35], 0x7300000
	s_or_b32 s24, s12, s36
	v_lshl_add_u64 v[226:227], v[224:225], 0, s[34:35]
	s_lshl_b64 s[24:25], s[24:25], 2
	v_lshl_add_u64 v[228:229], v[2:3], 0, s[24:25]
	global_load_dword v232, v[226:227], off offset:16
	s_nop 0
	global_load_dword v233, v[228:229], off offset:16
	v_add_co_u32_e32 v224, vcc, 0x7300000, v224
	s_nop 1
	v_addc_co_u32_e32 v225, vcc, 0, v225, vcc
	global_load_dword v234, v[224:225], off
	s_nop 0
	global_load_dword v235, v[228:229], off
	v_add_u32_e32 v224, s26, v208
	v_ashrrev_i32_e32 v225, 31, v224
	v_lshl_add_u64 v[224:225], v[224:225], 2, v[74:75]
	v_add_co_u32_e32 v224, vcc, 0x7382000, v224
	s_nop 1
	v_addc_co_u32_e32 v225, vcc, 0, v225, vcc
	global_load_dword v236, v[224:225], off
	s_mov_b64 exec, s[30:31]
	v_lshl_add_u64 v[6:7], v[20:21], 0, v[6:7]
	v_lshl_add_u64 v[4:5], v[20:21], 0, v[4:5]
	v_lshl_add_u64 v[6:7], v[6:7], 0, v[166:167]
	v_lshl_add_u64 v[4:5], v[4:5], 0, v[166:167]
	v_lshl_add_u64 v[6:7], v[6:7], 0, v[18:19]
	v_lshl_add_u64 v[4:5], v[4:5], 0, v[18:19]
	global_load_dword v158, v[6:7], off
	global_load_dword v156, v[6:7], off offset:512
	global_load_dword v154, v[6:7], off offset:1024
	global_load_dword v151, v[6:7], off offset:1536
	global_load_dword v149, v[6:7], off offset:2048
	global_load_dword v147, v[6:7], off offset:2560
	global_load_dword v145, v[6:7], off offset:3072
	global_load_dword v143, v[6:7], off offset:3584
	global_load_dword v157, v[4:5], off
	global_load_dword v155, v[4:5], off offset:512
	global_load_dword v153, v[4:5], off offset:1024
	global_load_dword v152, v[4:5], off offset:1536
	global_load_dword v150, v[4:5], off offset:2048
	global_load_dword v148, v[4:5], off offset:2560
	global_load_dword v146, v[4:5], off offset:3072
	global_load_dword v144, v[4:5], off offset:3584
	v_add_co_u32_e32 v6, vcc, s91, v6
	s_mov_b64 s[2:3], 0x800
	s_nop 0
	v_addc_co_u32_e32 v7, vcc, 0, v7, vcc
	v_add_co_u32_e32 v4, vcc, s91, v4
	v_add_u32_e32 v19, s6, v95
	s_nop 0
	v_addc_co_u32_e32 v5, vcc, 0, v5, vcc
	global_load_dword v141, v[6:7], off
	global_load_dword v139, v[6:7], off offset:512
	global_load_dword v137, v[6:7], off offset:1024
	global_load_dword v135, v[6:7], off offset:1536
	global_load_dword v133, v[6:7], off offset:2048
	global_load_dword v131, v[6:7], off offset:2560
	global_load_dword v129, v[6:7], off offset:3072
	global_load_dword v128, v[6:7], off offset:3584
	global_load_dword v142, v[4:5], off
	global_load_dword v140, v[4:5], off offset:512
	global_load_dword v138, v[4:5], off offset:1024
	global_load_dword v136, v[4:5], off offset:1536
	global_load_dword v134, v[4:5], off offset:2048
	global_load_dword v132, v[4:5], off offset:2560
	global_load_dword v130, v[4:5], off offset:3072
	global_load_dword v79, v[4:5], off offset:3584
	v_and_b32_e32 v4, 0xffffff80, v51
	v_ashrrev_i32_e32 v5, 31, v4
	v_lshlrev_b32_e32 v6, 4, v64
	v_add_u32_e32 v8, 0x1000, v4
	v_and_b32_e32 v10, 0xf0, v6
	v_lshlrev_b64 v[6:7], 1, v[4:5]
	v_ashrrev_i32_e32 v9, 31, v8
	v_or_b32_e32 v6, v6, v10
	v_lshlrev_b64 v[8:9], 1, v[8:9]
	v_lshl_add_u64 v[6:7], v[74:75], 0, v[6:7]
	v_or_b32_e32 v8, v8, v10
	v_lshl_add_u64 v[6:7], v[6:7], 0, s[14:15]
	v_lshl_add_u64 v[8:9], v[74:75], 0, v[8:9]
	v_lshl_add_u64 v[8:9], v[8:9], 0, s[14:15]
	global_load_dwordx4 v[36:39], v[6:7], off
	global_load_dwordx4 v[32:35], v[8:9], off
	v_add_u32_e32 v6, 0x2000, v4
	v_add_u32_e32 v4, 0x3000, v4
	v_ashrrev_i32_e32 v7, 31, v6
	v_ashrrev_i32_e32 v5, 31, v4
	v_lshlrev_b64 v[6:7], 1, v[6:7]
	v_lshlrev_b64 v[4:5], 1, v[4:5]
	v_or_b32_e32 v6, v6, v10
	v_or_b32_e32 v4, v4, v10
	v_lshl_add_u64 v[6:7], v[74:75], 0, v[6:7]
	v_lshl_add_u64 v[4:5], v[74:75], 0, v[4:5]
	v_lshl_add_u64 v[6:7], v[6:7], 0, s[14:15]
	v_lshl_add_u64 v[4:5], v[4:5], 0, s[14:15]
	global_load_dwordx4 v[44:47], v[6:7], off
	global_load_dwordx4 v[40:43], v[4:5], off
	v_lshlrev_b32_e32 v4, 2, v48
	v_mov_b32_e32 v5, v167
	s_waitcnt vmcnt(41)
	v_lshl_add_u64 v[0:1], v[0:1], 0, v[4:5]
	v_lshl_add_u64 v[4:5], v[0:1], 0, s[2:3]
	v_lshl_add_u64 v[8:9], v[0:1], 0, s[10:11]
	v_lshl_add_u64 v[14:15], v[4:5], 0, s[10:11]
	s_lshl_b64 s[10:11], s[20:21], 2
	v_lshl_add_u64 v[16:17], v[0:1], 0, s[10:11]
	v_lshl_add_u64 v[22:23], v[4:5], 0, s[10:11]
	s_lshl_b64 s[10:11], s[22:23], 2
	v_lshl_add_u64 v[6:7], s[16:17], 2, v[0:1]
	v_lshl_add_u64 v[4:5], v[4:5], 0, s[10:11]
	v_lshl_add_u64 v[24:25], v[0:1], 0, s[10:11]
	global_load_dwordx2 v[10:11], v[6:7], off
	global_load_dwordx2 v[12:13], v[8:9], off
	global_load_dwordx2 v[0:1], v[14:15], off
	s_nop 0
	global_load_dwordx2 v[6:7], v[6:7], off offset:2048
	s_nop 0
	global_load_dwordx2 v[16:17], v[16:17], off
	s_nop 0
	global_load_dwordx2 v[14:15], v[24:25], off
	s_nop 0
	global_load_dwordx2 v[4:5], v[4:5], off
	s_nop 0
	global_load_dwordx2 v[8:9], v[22:23], off
	v_cmp_gt_i32_e64 s[10:11], 3, v19
	s_and_saveexec_b64 s[6:7], s[10:11]
	s_xor_b64 s[6:7], exec, s[6:7]
	v_mov_b64_e32 v[30:31], s[96:97]
	s_or_saveexec_b64 s[6:7], s[6:7]
	v_add_u32_e32 v22, s13, v19
	v_ashrrev_i32_e32 v23, 31, v22
	v_lshl_add_u64 v[28:29], v[22:23], 0, -3
	v_lshl_add_u64 v[26:27], v[22:23], 0, -2
	v_lshl_add_u64 v[24:25], v[22:23], 0, -1
	v_mov_b32_e32 v100, 0
	v_alignbit_b32 v55, v29, v28, 8
	v_lshlrev_b32_e32 v54, 9, v28
	v_alignbit_b32 v53, v27, v26, 8
	v_lshlrev_b32_e32 v28, 9, v26
	v_alignbit_b32 v26, v25, v24, 8
	v_lshlrev_b32_e32 v19, 9, v24
	v_mov_b32_e32 v102, 0
	v_mov_b32_e32 v103, 0
	s_xor_b64 exec, exec, s[6:7]
	s_cbranch_execz .LBB0_1157
	v_mad_u64_u32 v[56:57], s[24:25], v55, 49, s[96:97]
	v_mad_u32_u24 v57, v29, 49, v57
	v_lshlrev_b64 v[56:57], 17, v[56:57]
	v_lshl_add_u64 v[56:57], v[20:21], 0, v[56:57]
	v_and_b32_e32 v58, 0x1fe00, v54
	v_mov_b32_e32 v59, v167
	v_lshl_add_u64 v[56:57], v[56:57], 0, v[58:59]
	v_lshl_add_u64 v[56:57], v[56:57], 0, v[166:167]
	global_load_dword v100, v[56:57], off
	v_mad_u64_u32 v[56:57], s[24:25], v53, 49, s[96:97]
	v_mad_u32_u24 v57, v27, 49, v57
	v_lshlrev_b64 v[56:57], 17, v[56:57]
	v_lshl_add_u64 v[56:57], v[20:21], 0, v[56:57]
	v_and_b32_e32 v58, 0x1fe00, v28
	v_lshl_add_u64 v[56:57], v[56:57], 0, v[58:59]
	v_lshl_add_u64 v[56:57], v[56:57], 0, v[166:167]
	global_load_dword v102, v[56:57], off
	v_mad_u64_u32 v[56:57], s[24:25], v26, 49, s[96:97]
	v_mad_u32_u24 v57, v25, 49, v57
	v_lshlrev_b64 v[56:57], 17, v[56:57]
	v_lshl_add_u64 v[56:57], v[20:21], 0, v[56:57]
	v_and_b32_e32 v58, 0x1fe00, v19
	v_lshl_add_u64 v[56:57], v[56:57], 0, v[58:59]
	v_lshl_add_u64 v[56:57], v[56:57], 0, v[166:167]
	global_load_dword v103, v[56:57], off

.LBB0_1169:
	s_or_b64 exec, exec, s[6:7]
	s_waitcnt lgkmcnt(0)
	s_barrier
	s_waitcnt vmcnt(50)
	v_lshlrev_b32_e32 v18, 16, v100
	v_and_b32_e32 v19, 0xffff0000, v100
	s_waitcnt vmcnt(47)
	v_lshlrev_b32_e32 v106, 16, v104
	v_and_b32_e32 v107, 0xffff0000, v104
	v_pk_fma_f32 v[18:19], v[10:11], v[18:19], 0 op_sel_hi:[1,1,0]
	v_lshlrev_b32_e32 v104, 16, v102
	v_and_b32_e32 v105, 0xffff0000, v102
	v_pk_fma_f32 v[18:19], v[12:13], v[104:105], v[18:19]
	v_lshlrev_b32_e32 v102, 16, v103
	v_and_b32_e32 v103, 0xffff0000, v103
	v_pk_fma_f32 v[18:19], v[16:17], v[102:103], v[18:19]
	s_mov_b32 s2, 0x3db504f3
	v_pk_fma_f32 v[18:19], v[14:15], v[106:107], v[18:19]
	v_pk_fma_f32 v[104:105], v[10:11], v[104:105], 0 op_sel_hi:[1,1,0]
	v_mul_f32_e32 v3, 0xbfb8aa3b, v18
	v_exp_f32_e32 v3, v3
	v_pk_fma_f32 v[104:105], v[12:13], v[102:103], v[104:105]
	v_lshl_add_u32 v2, v160, 1, 0
	s_movk_i32 s0, 0x1100
	v_add_f32_e32 v3, 1.0, v3
	v_rcp_f32_e32 v108, v3
	v_mul_f32_e32 v3, 0xbfb8aa3b, v19
	v_exp_f32_e32 v3, v3
	s_waitcnt vmcnt(46)
	v_lshlrev_b32_e32 v100, 16, v101
	v_and_b32_e32 v101, 0xffff0000, v101
	v_pk_fma_f32 v[104:105], v[16:17], v[106:107], v[104:105]
	v_add_f32_e32 v3, 1.0, v3
	v_rcp_f32_e32 v109, v3
	v_pk_fma_f32 v[104:105], v[14:15], v[100:101], v[104:105]
	v_pk_fma_f32 v[102:103], v[10:11], v[102:103], 0 op_sel_hi:[1,1,0]
	v_or_b32_e32 v161, 1, v95
	v_pk_mul_f32 v[18:19], v[18:19], v[108:109]
	v_pk_fma_f32 v[102:103], v[12:13], v[106:107], v[102:103]
	v_pk_mul_f32 v[18:19], v[18:19], s[2:3] op_sel_hi:[1,0]
	v_pk_fma_f32 v[102:103], v[16:17], v[100:101], v[102:103]
	v_cvt_pk_bf16_f32 v3, v18, v19
	v_mad_u64_u32 v[18:19], s[6:7], v159, s0, v[2:3]
	ds_write_b32 v18, v3 offset:2048
	v_mul_f32_e32 v3, 0xbfb8aa3b, v104
	v_exp_f32_e32 v3, v3
	s_nop 0
	v_add_f32_e32 v3, 1.0, v3
	v_rcp_f32_e32 v108, v3
	v_mul_f32_e32 v3, 0xbfb8aa3b, v105
	v_exp_f32_e32 v3, v3
	s_nop 0
	v_add_f32_e32 v3, 1.0, v3
	v_rcp_f32_e32 v109, v3
	v_mad_u64_u32 v[2:3], s[6:7], v161, s50, v[2:3]
	v_add_u32_e32 v95, 0x800, v2
	v_pk_mul_f32 v[104:105], v[104:105], v[108:109]
	s_nop 0
	v_pk_mul_f32 v[104:105], v[104:105], s[2:3] op_sel_hi:[1,0]
	s_nop 0
	v_cvt_pk_bf16_f32 v19, v104, v105
	s_waitcnt vmcnt(45)
	v_lshlrev_b32_e32 v104, 16, v99
	v_and_b32_e32 v105, 0xffff0000, v99
	v_pk_fma_f32 v[102:103], v[14:15], v[104:105], v[102:103]
	s_nop 0
	v_mul_f32_e32 v3, 0xbfb8aa3b, v102
	v_exp_f32_e32 v3, v3
	s_nop 0
	v_add_f32_e32 v3, 1.0, v3
	v_rcp_f32_e32 v108, v3
	v_mul_f32_e32 v3, 0xbfb8aa3b, v103
	v_exp_f32_e32 v3, v3
	s_nop 0
	v_add_f32_e32 v3, 1.0, v3
	v_rcp_f32_e32 v109, v3
	s_nop 0
	v_pk_mul_f32 v[102:103], v[102:103], v[108:109]
	s_nop 0
	v_pk_mul_f32 v[102:103], v[102:103], s[2:3] op_sel_hi:[1,0]
	s_nop 0
	v_cvt_pk_bf16_f32 v3, v102, v103
	s_waitcnt vmcnt(44)
	v_lshlrev_b32_e32 v102, 16, v98
	v_and_b32_e32 v103, 0xffff0000, v98
	v_pk_fma_f32 v[98:99], v[10:11], v[106:107], 0 op_sel_hi:[1,1,0]
	ds_write2_b32 v95, v19, v3 offset1:68
	v_pk_fma_f32 v[98:99], v[12:13], v[100:101], v[98:99]
	s_nop 0
	v_pk_fma_f32 v[98:99], v[16:17], v[104:105], v[98:99]
	s_nop 0
	v_pk_fma_f32 v[98:99], v[14:15], v[102:103], v[98:99]
	s_nop 0
	v_mul_f32_e32 v3, 0xbfb8aa3b, v98
	v_exp_f32_e32 v3, v3
	s_nop 0
	v_add_f32_e32 v3, 1.0, v3
	v_rcp_f32_e32 v106, v3
	v_mul_f32_e32 v3, 0xbfb8aa3b, v99
	v_exp_f32_e32 v3, v3
	s_nop 0
	v_add_f32_e32 v3, 1.0, v3
	v_rcp_f32_e32 v107, v3
	s_nop 0
	v_pk_mul_f32 v[98:99], v[98:99], v[106:107]
	s_nop 0
	v_pk_mul_f32 v[98:99], v[98:99], s[2:3] op_sel_hi:[1,0]
	s_nop 0
	v_cvt_pk_bf16_f32 v3, v98, v99
	ds_write_b32 v2, v3 offset:2592
	v_pk_fma_f32 v[100:101], v[10:11], v[100:101], 0 op_sel_hi:[1,1,0]
	s_waitcnt vmcnt(43)
	v_lshlrev_b32_e32 v98, 16, v97
	v_pk_fma_f32 v[100:101], v[12:13], v[104:105], v[100:101]
	v_and_b32_e32 v99, 0xffff0000, v97
	v_pk_fma_f32 v[100:101], v[16:17], v[102:103], v[100:101]
	v_add_u32_e32 v95, 0xa00, v2
	v_pk_fma_f32 v[100:101], v[14:15], v[98:99], v[100:101]
	s_nop 0
	v_mul_f32_e32 v3, 0xbfb8aa3b, v100
	v_exp_f32_e32 v3, v3
	s_nop 0
	v_add_f32_e32 v3, 1.0, v3
	v_rcp_f32_e32 v106, v3
	v_mul_f32_e32 v3, 0xbfb8aa3b, v101
	v_exp_f32_e32 v3, v3
	s_nop 0
	v_add_f32_e32 v3, 1.0, v3
	v_rcp_f32_e32 v107, v3
	s_nop 0
	v_pk_mul_f32 v[100:101], v[100:101], v[106:107]
	s_nop 0
	v_pk_mul_f32 v[100:101], v[100:101], s[2:3] op_sel_hi:[1,0]
	s_nop 0
	v_cvt_pk_bf16_f32 v3, v100, v101
	s_waitcnt vmcnt(42)
	v_lshlrev_b32_e32 v100, 16, v96
	v_and_b32_e32 v101, 0xffff0000, v96
	v_pk_fma_f32 v[96:97], v[10:11], v[104:105], 0 op_sel_hi:[1,1,0]
	s_nop 0
	v_pk_fma_f32 v[96:97], v[12:13], v[102:103], v[96:97]
	s_nop 0
	v_pk_fma_f32 v[96:97], v[16:17], v[98:99], v[96:97]
	s_nop 0
	v_pk_fma_f32 v[96:97], v[14:15], v[100:101], v[96:97]
	s_nop 0
	v_mul_f32_e32 v19, 0xbfb8aa3b, v96
	v_exp_f32_e32 v19, v19
	s_nop 0
	v_add_f32_e32 v19, 1.0, v19
	v_rcp_f32_e32 v104, v19
	v_mul_f32_e32 v19, 0xbfb8aa3b, v97
	v_exp_f32_e32 v19, v19
	s_nop 0
	v_add_f32_e32 v19, 1.0, v19
	v_rcp_f32_e32 v105, v19
	s_nop 0
	v_pk_mul_f32 v[96:97], v[96:97], v[104:105]
	s_nop 0
	v_pk_mul_f32 v[96:97], v[96:97], s[2:3] op_sel_hi:[1,0]
	s_nop 0
	v_cvt_pk_bf16_f32 v19, v96, v97
	ds_write2_b32 v95, v3, v19 offset0:76 offset1:144
	s_waitcnt vmcnt(41)
	v_lshlrev_b32_e32 v96, 16, v94
	v_and_b32_e32 v97, 0xffff0000, v94
	v_pk_fma_f32 v[94:95], v[10:11], v[102:103], 0 op_sel_hi:[1,1,0]
	s_nop 0
	v_pk_fma_f32 v[94:95], v[12:13], v[98:99], v[94:95]
	v_pk_fma_f32 v[98:99], v[10:11], v[98:99], 0 op_sel_hi:[1,1,0]
	v_pk_fma_f32 v[94:95], v[16:17], v[100:101], v[94:95]
	v_pk_fma_f32 v[98:99], v[12:13], v[100:101], v[98:99]
	v_pk_fma_f32 v[94:95], v[14:15], v[96:97], v[94:95]
	v_pk_fma_f32 v[98:99], v[16:17], v[96:97], v[98:99]
	v_mul_f32_e32 v3, 0xbfb8aa3b, v94
	v_exp_f32_e32 v3, v3
	s_nop 0
	v_add_f32_e32 v3, 1.0, v3
	v_rcp_f32_e32 v102, v3
	v_mul_f32_e32 v3, 0xbfb8aa3b, v95
	v_exp_f32_e32 v3, v3
	s_nop 0
	v_add_f32_e32 v3, 1.0, v3
	v_rcp_f32_e32 v103, v3
	s_nop 0
	v_pk_mul_f32 v[94:95], v[94:95], v[102:103]
	s_nop 0
	v_pk_mul_f32 v[94:95], v[94:95], s[2:3] op_sel_hi:[1,0]
	s_nop 0
	v_cvt_pk_bf16_f32 v3, v94, v95
	s_waitcnt vmcnt(40)
	v_lshlrev_b32_e32 v94, 16, v93
	v_and_b32_e32 v95, 0xffff0000, v93
	v_pk_fma_f32 v[98:99], v[14:15], v[94:95], v[98:99]
	v_add_u32_e32 v93, 0xc00, v2
	v_mul_f32_e32 v19, 0xbfb8aa3b, v98
	v_exp_f32_e32 v19, v19
	s_nop 0
	v_add_f32_e32 v19, 1.0, v19
	v_rcp_f32_e32 v102, v19
	v_mul_f32_e32 v19, 0xbfb8aa3b, v99
	v_exp_f32_e32 v19, v19
	s_nop 0
	v_add_f32_e32 v19, 1.0, v19
	v_rcp_f32_e32 v103, v19
	s_nop 0
	v_pk_mul_f32 v[98:99], v[98:99], v[102:103]
	s_nop 0
	v_pk_mul_f32 v[98:99], v[98:99], s[2:3] op_sel_hi:[1,0]
	s_nop 0
	v_cvt_pk_bf16_f32 v19, v98, v99
	ds_write2_b32 v93, v3, v19 offset0:84 offset1:152
	s_waitcnt vmcnt(39)
	v_lshlrev_b32_e32 v98, 16, v92
	v_and_b32_e32 v99, 0xffff0000, v92
	v_pk_fma_f32 v[92:93], v[10:11], v[100:101], 0 op_sel_hi:[1,1,0]
	s_nop 0
	v_pk_fma_f32 v[92:93], v[12:13], v[96:97], v[92:93]
	v_pk_fma_f32 v[96:97], v[10:11], v[96:97], 0 op_sel_hi:[1,1,0]
	v_pk_fma_f32 v[92:93], v[16:17], v[94:95], v[92:93]
	v_pk_fma_f32 v[96:97], v[12:13], v[94:95], v[96:97]
	v_pk_fma_f32 v[92:93], v[14:15], v[98:99], v[92:93]
	v_pk_fma_f32 v[96:97], v[16:17], v[98:99], v[96:97]
	v_mul_f32_e32 v3, 0xbfb8aa3b, v92
	v_exp_f32_e32 v3, v3
	s_nop 0
	v_add_f32_e32 v3, 1.0, v3
	v_rcp_f32_e32 v100, v3
	v_mul_f32_e32 v3, 0xbfb8aa3b, v93
	v_exp_f32_e32 v3, v3
	s_nop 0
	v_add_f32_e32 v3, 1.0, v3
	v_rcp_f32_e32 v101, v3
	s_nop 0
	v_pk_mul_f32 v[92:93], v[92:93], v[100:101]
	s_nop 0
	v_pk_mul_f32 v[92:93], v[92:93], s[2:3] op_sel_hi:[1,0]
	s_nop 0
	v_cvt_pk_bf16_f32 v3, v92, v93
	s_waitcnt vmcnt(38)
	v_lshlrev_b32_e32 v92, 16, v91
	v_and_b32_e32 v93, 0xffff0000, v91
	v_pk_fma_f32 v[96:97], v[14:15], v[92:93], v[96:97]
	v_add_u32_e32 v91, 0xe00, v2
	v_mul_f32_e32 v19, 0xbfb8aa3b, v96
	v_exp_f32_e32 v19, v19
	s_nop 0
	v_add_f32_e32 v19, 1.0, v19
	v_rcp_f32_e32 v100, v19
	v_mul_f32_e32 v19, 0xbfb8aa3b, v97
	v_exp_f32_e32 v19, v19
	s_nop 0
	v_add_f32_e32 v19, 1.0, v19
	v_rcp_f32_e32 v101, v19
	s_nop 0
	v_pk_mul_f32 v[96:97], v[96:97], v[100:101]
	s_nop 0
	v_pk_mul_f32 v[96:97], v[96:97], s[2:3] op_sel_hi:[1,0]
	s_nop 0
	v_cvt_pk_bf16_f32 v19, v96, v97
	ds_write2_b32 v91, v3, v19 offset0:92 offset1:160
	s_waitcnt vmcnt(37)
	v_lshlrev_b32_e32 v96, 16, v90
	v_and_b32_e32 v97, 0xffff0000, v90
	v_pk_fma_f32 v[90:91], v[10:11], v[94:95], 0 op_sel_hi:[1,1,0]
	s_nop 0
	v_pk_fma_f32 v[90:91], v[12:13], v[98:99], v[90:91]
	s_nop 0
	v_pk_fma_f32 v[90:91], v[16:17], v[92:93], v[90:91]
	s_nop 0
	v_pk_fma_f32 v[90:91], v[14:15], v[96:97], v[90:91]
	s_nop 0
	v_mul_f32_e32 v3, 0xbfb8aa3b, v90
	v_exp_f32_e32 v3, v3
	s_nop 0
	v_add_f32_e32 v3, 1.0, v3
	v_rcp_f32_e32 v94, v3
	v_mul_f32_e32 v3, 0xbfb8aa3b, v91
	v_exp_f32_e32 v3, v3
	s_nop 0
	v_add_f32_e32 v3, 1.0, v3
	v_rcp_f32_e32 v95, v3
	s_nop 0
	v_pk_mul_f32 v[90:91], v[90:91], v[94:95]
	v_pk_fma_f32 v[94:95], v[10:11], v[98:99], 0 op_sel_hi:[1,1,0]
	v_pk_mul_f32 v[90:91], v[90:91], s[2:3] op_sel_hi:[1,0]
	v_pk_fma_f32 v[94:95], v[12:13], v[92:93], v[94:95]
	v_cvt_pk_bf16_f32 v3, v90, v91
	s_waitcnt vmcnt(36)
	v_lshlrev_b32_e32 v90, 16, v89
	v_and_b32_e32 v91, 0xffff0000, v89
	v_pk_fma_f32 v[94:95], v[16:17], v[96:97], v[94:95]
	v_add_u32_e32 v89, 0x1000, v2
	v_pk_fma_f32 v[94:95], v[14:15], v[90:91], v[94:95]
	s_nop 0
	v_mul_f32_e32 v19, 0xbfb8aa3b, v94
	v_exp_f32_e32 v19, v19
	s_nop 0
	v_add_f32_e32 v19, 1.0, v19
	v_rcp_f32_e32 v98, v19
	v_mul_f32_e32 v19, 0xbfb8aa3b, v95
	v_exp_f32_e32 v19, v19
	s_nop 0
	v_add_f32_e32 v19, 1.0, v19
	v_rcp_f32_e32 v99, v19
	s_nop 0
	v_pk_mul_f32 v[94:95], v[94:95], v[98:99]
	s_nop 0
	v_pk_mul_f32 v[94:95], v[94:95], s[2:3] op_sel_hi:[1,0]
	s_nop 0
	v_cvt_pk_bf16_f32 v19, v94, v95
	ds_write2_b32 v89, v3, v19 offset0:100 offset1:168
	s_waitcnt vmcnt(35)
	v_lshlrev_b32_e32 v94, 16, v88
	v_and_b32_e32 v95, 0xffff0000, v88
	v_pk_fma_f32 v[88:89], v[10:11], v[92:93], 0 op_sel_hi:[1,1,0]
	s_nop 0
	v_pk_fma_f32 v[88:89], v[12:13], v[96:97], v[88:89]
	s_nop 0
	v_pk_fma_f32 v[88:89], v[16:17], v[90:91], v[88:89]
	s_nop 0
	v_pk_fma_f32 v[88:89], v[14:15], v[94:95], v[88:89]
	s_nop 0
	v_mul_f32_e32 v3, 0xbfb8aa3b, v88
	v_exp_f32_e32 v3, v3
	s_nop 0
	v_add_f32_e32 v3, 1.0, v3
	v_rcp_f32_e32 v92, v3
	v_mul_f32_e32 v3, 0xbfb8aa3b, v89
	v_exp_f32_e32 v3, v3
	s_nop 0
	v_add_f32_e32 v3, 1.0, v3
	v_rcp_f32_e32 v93, v3
	s_nop 0
	v_pk_mul_f32 v[88:89], v[88:89], v[92:93]
	v_pk_fma_f32 v[92:93], v[10:11], v[96:97], 0 op_sel_hi:[1,1,0]
	v_pk_mul_f32 v[88:89], v[88:89], s[2:3] op_sel_hi:[1,0]
	v_pk_fma_f32 v[92:93], v[12:13], v[90:91], v[92:93]
	v_cvt_pk_bf16_f32 v3, v88, v89
	s_waitcnt vmcnt(34)
	v_lshlrev_b32_e32 v88, 16, v87
	v_and_b32_e32 v89, 0xffff0000, v87
	v_pk_fma_f32 v[92:93], v[16:17], v[94:95], v[92:93]
	v_pk_fma_f32 v[90:91], v[10:11], v[90:91], 0 op_sel_hi:[1,1,0]
	v_pk_fma_f32 v[92:93], v[14:15], v[88:89], v[92:93]
	v_pk_fma_f32 v[90:91], v[12:13], v[94:95], v[90:91]
	v_mul_f32_e32 v19, 0xbfb8aa3b, v92
	v_exp_f32_e32 v19, v19
	v_pk_fma_f32 v[90:91], v[16:17], v[88:89], v[90:91]
	v_add_u32_e32 v87, 0x1200, v2
	v_pk_fma_f32 v[10:11], v[10:11], v[94:95], 0 op_sel_hi:[1,1,0]
	v_add_f32_e32 v19, 1.0, v19
	v_rcp_f32_e32 v96, v19
	v_mul_f32_e32 v19, 0xbfb8aa3b, v93
	v_exp_f32_e32 v19, v19
	v_pk_fma_f32 v[10:11], v[12:13], v[88:89], v[10:11]
	v_add_f32_e32 v19, 1.0, v19
	v_rcp_f32_e32 v97, v19
	s_nop 0
	v_pk_mul_f32 v[92:93], v[92:93], v[96:97]
	s_nop 0
	v_pk_mul_f32 v[92:93], v[92:93], s[2:3] op_sel_hi:[1,0]
	s_nop 0
	v_cvt_pk_bf16_f32 v19, v92, v93
	s_waitcnt vmcnt(33)
	v_lshlrev_b32_e32 v92, 16, v85
	v_and_b32_e32 v93, 0xffff0000, v85
	v_pk_fma_f32 v[90:91], v[14:15], v[92:93], v[90:91]
	ds_write2_b32 v87, v3, v19 offset0:108 offset1:176
	v_mul_f32_e32 v3, 0xbfb8aa3b, v90
	v_exp_f32_e32 v3, v3
	v_pk_fma_f32 v[10:11], v[16:17], v[92:93], v[10:11]
	v_add_f32_e32 v3, 1.0, v3
	v_rcp_f32_e32 v96, v3
	v_mul_f32_e32 v3, 0xbfb8aa3b, v91
	v_exp_f32_e32 v3, v3
	s_nop 0
	v_add_f32_e32 v3, 1.0, v3
	v_rcp_f32_e32 v97, v3
	s_nop 0
	v_pk_mul_f32 v[90:91], v[90:91], v[96:97]
	s_nop 0
	v_pk_mul_f32 v[90:91], v[90:91], s[2:3] op_sel_hi:[1,0]
	s_nop 0
	v_cvt_pk_bf16_f32 v3, v90, v91
	s_waitcnt vmcnt(32)
	v_lshlrev_b32_e32 v90, 16, v69
	v_and_b32_e32 v91, 0xffff0000, v69
	v_pk_fma_f32 v[10:11], v[14:15], v[90:91], v[10:11]
	s_nop 0
	v_mul_f32_e32 v12, 0xbfb8aa3b, v10
	v_mul_f32_e32 v13, 0xbfb8aa3b, v11
	v_exp_f32_e32 v12, v12
	v_exp_f32_e32 v13, v13
	v_add_f32_e32 v12, 1.0, v12
	v_add_f32_e32 v13, 1.0, v13
	v_rcp_f32_e32 v12, v12
	v_rcp_f32_e32 v13, v13
	s_nop 0
	v_pk_mul_f32 v[10:11], v[10:11], v[12:13]
	s_nop 0
	v_pk_mul_f32 v[10:11], v[10:11], s[2:3] op_sel_hi:[1,0]
	s_nop 0
	v_cvt_pk_bf16_f32 v10, v10, v11
	v_add_u32_e32 v11, 0x1400, v2
	ds_write2_b32 v11, v3, v10 offset0:116 offset1:184
	v_lshlrev_b32_e32 v10, 16, v71
	v_and_b32_e32 v11, 0xffff0000, v71
	v_lshlrev_b32_e32 v12, 16, v78
	v_and_b32_e32 v13, 0xffff0000, v78
	v_pk_fma_f32 v[10:11], v[6:7], v[10:11], 0 op_sel_hi:[1,1,0]
	v_lshlrev_b32_e32 v14, 16, v84
	v_and_b32_e32 v15, 0xffff0000, v84
	v_pk_fma_f32 v[10:11], v[0:1], v[12:13], v[10:11]
	s_waitcnt vmcnt(31)
	v_lshlrev_b32_e32 v16, 16, v86
	v_and_b32_e32 v17, 0xffff0000, v86
	v_pk_fma_f32 v[10:11], v[8:9], v[14:15], v[10:11]
	v_pk_fma_f32 v[12:13], v[6:7], v[12:13], 0 op_sel_hi:[1,1,0]
	v_pk_fma_f32 v[10:11], v[4:5], v[16:17], v[10:11]
	v_pk_fma_f32 v[12:13], v[0:1], v[14:15], v[12:13]
	v_mul_f32_e32 v3, 0xbfb8aa3b, v10
	v_exp_f32_e32 v3, v3
	v_pk_fma_f32 v[12:13], v[8:9], v[16:17], v[12:13]
	v_pk_fma_f32 v[14:15], v[6:7], v[14:15], 0 op_sel_hi:[1,1,0]
	v_add_f32_e32 v3, 1.0, v3
	v_rcp_f32_e32 v84, v3
	v_mul_f32_e32 v3, 0xbfb8aa3b, v11
	v_exp_f32_e32 v3, v3
	v_pk_fma_f32 v[14:15], v[0:1], v[16:17], v[14:15]
	v_pk_fma_f32 v[16:17], v[6:7], v[16:17], 0 op_sel_hi:[1,1,0]
	v_add_f32_e32 v3, 1.0, v3
	v_rcp_f32_e32 v85, v3
	s_nop 0
	v_pk_mul_f32 v[10:11], v[10:11], v[84:85]
	s_nop 0
	v_cvt_pk_bf16_f32 v3, v10, v11
	s_waitcnt vmcnt(30)
	v_lshlrev_b32_e32 v10, 16, v70
	v_and_b32_e32 v11, 0xffff0000, v70
	v_pk_fma_f32 v[12:13], v[4:5], v[10:11], v[12:13]
	ds_write_b32 v18, v3 offset:36864
	v_mul_f32_e32 v3, 0xbfb8aa3b, v12
	v_exp_f32_e32 v3, v3
	v_pk_fma_f32 v[14:15], v[8:9], v[10:11], v[14:15]
	v_pk_fma_f32 v[16:17], v[0:1], v[10:11], v[16:17]
	v_add_f32_e32 v3, 1.0, v3
	v_rcp_f32_e32 v18, v3
	v_mul_f32_e32 v3, 0xbfb8aa3b, v13
	v_exp_f32_e32 v3, v3
	s_nop 0
	v_add_f32_e32 v3, 1.0, v3
	v_rcp_f32_e32 v19, v3
	s_nop 0
	v_pk_mul_f32 v[12:13], v[12:13], v[18:19]
	s_nop 0
	v_cvt_pk_bf16_f32 v3, v12, v13
	s_waitcnt vmcnt(29)
	v_lshlrev_b32_e32 v12, 16, v68
	v_and_b32_e32 v13, 0xffff0000, v68
	v_pk_fma_f32 v[14:15], v[4:5], v[12:13], v[14:15]
	v_pk_fma_f32 v[16:17], v[8:9], v[12:13], v[16:17]
	v_mul_f32_e32 v18, 0xbfb8aa3b, v14
	v_mul_f32_e32 v19, 0xbfb8aa3b, v15
	v_exp_f32_e32 v18, v18
	v_exp_f32_e32 v19, v19
	v_add_f32_e32 v18, 1.0, v18
	v_add_f32_e32 v19, 1.0, v19
	v_rcp_f32_e32 v18, v18
	v_rcp_f32_e32 v19, v19
	s_nop 0
	v_pk_mul_f32 v[14:15], v[14:15], v[18:19]
	s_nop 0
	v_cvt_pk_bf16_f32 v14, v14, v15
	v_add_u32_e32 v15, 0x9000, v2
	ds_write2_b32 v15, v3, v14 offset1:68
	s_waitcnt vmcnt(28)
	v_lshlrev_b32_e32 v14, 16, v67
	v_and_b32_e32 v15, 0xffff0000, v67
	v_pk_fma_f32 v[16:17], v[4:5], v[14:15], v[16:17]
	s_nop 0
	v_mul_f32_e32 v3, 0xbfb8aa3b, v16
	v_exp_f32_e32 v3, v3
	s_nop 0
	v_add_f32_e32 v3, 1.0, v3
	v_rcp_f32_e32 v18, v3
	v_mul_f32_e32 v3, 0xbfb8aa3b, v17
	v_exp_f32_e32 v3, v3
	s_nop 0
	v_add_f32_e32 v3, 1.0, v3
	v_rcp_f32_e32 v19, v3
	s_nop 0
	v_pk_mul_f32 v[16:17], v[16:17], v[18:19]
	s_nop 0
	v_cvt_pk_bf16_f32 v3, v16, v17
	ds_write_b32 v2, v3 offset:37408
	v_pk_fma_f32 v[10:11], v[6:7], v[10:11], 0 op_sel_hi:[1,1,0]
	s_waitcnt vmcnt(27)
	v_lshlrev_b32_e32 v16, 16, v66
	v_pk_fma_f32 v[10:11], v[0:1], v[12:13], v[10:11]
	v_and_b32_e32 v17, 0xffff0000, v66
	v_pk_fma_f32 v[10:11], v[8:9], v[14:15], v[10:11]
	v_pk_fma_f32 v[12:13], v[6:7], v[12:13], 0 op_sel_hi:[1,1,0]
	v_pk_fma_f32 v[10:11], v[4:5], v[16:17], v[10:11]
	v_pk_fma_f32 v[12:13], v[0:1], v[14:15], v[12:13]
	v_mul_f32_e32 v3, 0xbfb8aa3b, v10
	v_exp_f32_e32 v3, v3
	v_pk_fma_f32 v[12:13], v[8:9], v[16:17], v[12:13]
	v_pk_fma_f32 v[14:15], v[6:7], v[14:15], 0 op_sel_hi:[1,1,0]
	v_add_f32_e32 v3, 1.0, v3
	v_rcp_f32_e32 v18, v3
	v_mul_f32_e32 v3, 0xbfb8aa3b, v11
	v_exp_f32_e32 v3, v3
	v_pk_fma_f32 v[14:15], v[0:1], v[16:17], v[14:15]
	v_pk_fma_f32 v[16:17], v[6:7], v[16:17], 0 op_sel_hi:[1,1,0]
	v_add_f32_e32 v3, 1.0, v3
	v_rcp_f32_e32 v19, v3
	s_nop 0
	v_pk_mul_f32 v[10:11], v[10:11], v[18:19]
	s_nop 0
	v_cvt_pk_bf16_f32 v3, v10, v11
	s_waitcnt vmcnt(26)
	v_lshlrev_b32_e32 v10, 16, v65
	v_and_b32_e32 v11, 0xffff0000, v65
	v_pk_fma_f32 v[12:13], v[4:5], v[10:11], v[12:13]
	v_pk_fma_f32 v[14:15], v[8:9], v[10:11], v[14:15]
	v_mul_f32_e32 v18, 0xbfb8aa3b, v12
	v_mul_f32_e32 v19, 0xbfb8aa3b, v13
	v_exp_f32_e32 v18, v18
	v_exp_f32_e32 v19, v19
	v_pk_fma_f32 v[16:17], v[0:1], v[10:11], v[16:17]
	v_add_f32_e32 v18, 1.0, v18
	v_add_f32_e32 v19, 1.0, v19
	v_rcp_f32_e32 v18, v18
	v_rcp_f32_e32 v19, v19
	s_nop 0
	v_pk_mul_f32 v[12:13], v[12:13], v[18:19]
	s_nop 0
	v_cvt_pk_bf16_f32 v12, v12, v13
	v_add_u32_e32 v13, 0x9200, v2
	ds_write2_b32 v13, v3, v12 offset0:76 offset1:144
	s_waitcnt vmcnt(25)
	v_lshlrev_b32_e32 v12, 16, v63
	v_and_b32_e32 v13, 0xffff0000, v63
	v_pk_fma_f32 v[14:15], v[4:5], v[12:13], v[14:15]
	v_pk_fma_f32 v[16:17], v[8:9], v[12:13], v[16:17]
	v_mul_f32_e32 v3, 0xbfb8aa3b, v14
	v_exp_f32_e32 v3, v3
	s_nop 0
	v_add_f32_e32 v3, 1.0, v3
	v_rcp_f32_e32 v18, v3
	v_mul_f32_e32 v3, 0xbfb8aa3b, v15
	v_exp_f32_e32 v3, v3
	s_nop 0
	v_add_f32_e32 v3, 1.0, v3
	v_rcp_f32_e32 v19, v3
	s_nop 0
	v_pk_mul_f32 v[14:15], v[14:15], v[18:19]
	s_nop 0
	v_cvt_pk_bf16_f32 v3, v14, v15
	s_waitcnt vmcnt(24)
	v_lshlrev_b32_e32 v14, 16, v62
	v_and_b32_e32 v15, 0xffff0000, v62
	v_pk_fma_f32 v[16:17], v[4:5], v[14:15], v[16:17]
	s_nop 0
	v_mul_f32_e32 v18, 0xbfb8aa3b, v16
	v_mul_f32_e32 v19, 0xbfb8aa3b, v17
	v_exp_f32_e32 v18, v18
	v_exp_f32_e32 v19, v19
	v_add_f32_e32 v18, 1.0, v18
	v_add_f32_e32 v19, 1.0, v19
	v_rcp_f32_e32 v18, v18
	v_rcp_f32_e32 v19, v19
	s_nop 0
	v_pk_mul_f32 v[16:17], v[16:17], v[18:19]
	s_nop 0
	v_cvt_pk_bf16_f32 v16, v16, v17
	v_add_u32_e32 v17, 0x9400, v2
	ds_write2_b32 v17, v3, v16 offset0:84 offset1:152
	v_pk_fma_f32 v[10:11], v[6:7], v[10:11], 0 op_sel_hi:[1,1,0]
	s_waitcnt vmcnt(23)
	v_lshlrev_b32_e32 v16, 16, v61
	v_pk_fma_f32 v[10:11], v[0:1], v[12:13], v[10:11]
	v_and_b32_e32 v17, 0xffff0000, v61
	v_pk_fma_f32 v[10:11], v[8:9], v[14:15], v[10:11]
	v_pk_fma_f32 v[12:13], v[6:7], v[12:13], 0 op_sel_hi:[1,1,0]
	v_pk_fma_f32 v[10:11], v[4:5], v[16:17], v[10:11]
	v_pk_fma_f32 v[12:13], v[0:1], v[14:15], v[12:13]
	v_mul_f32_e32 v3, 0xbfb8aa3b, v10
	v_exp_f32_e32 v3, v3
	v_pk_fma_f32 v[12:13], v[8:9], v[16:17], v[12:13]
	v_pk_fma_f32 v[14:15], v[6:7], v[14:15], 0 op_sel_hi:[1,1,0]
	v_add_f32_e32 v3, 1.0, v3
	v_rcp_f32_e32 v18, v3
	v_mul_f32_e32 v3, 0xbfb8aa3b, v11
	v_exp_f32_e32 v3, v3
	v_pk_fma_f32 v[14:15], v[0:1], v[16:17], v[14:15]
	v_pk_fma_f32 v[16:17], v[6:7], v[16:17], 0 op_sel_hi:[1,1,0]
	v_add_f32_e32 v3, 1.0, v3
	v_rcp_f32_e32 v19, v3
	s_nop 0
	v_pk_mul_f32 v[10:11], v[10:11], v[18:19]
	s_nop 0
	v_cvt_pk_bf16_f32 v3, v10, v11
	s_waitcnt vmcnt(22)
	v_lshlrev_b32_e32 v10, 16, v60
	v_and_b32_e32 v11, 0xffff0000, v60
	v_pk_fma_f32 v[12:13], v[4:5], v[10:11], v[12:13]
	v_pk_fma_f32 v[14:15], v[8:9], v[10:11], v[14:15]
	v_mul_f32_e32 v18, 0xbfb8aa3b, v12
	v_mul_f32_e32 v19, 0xbfb8aa3b, v13
	v_exp_f32_e32 v18, v18
	v_exp_f32_e32 v19, v19
	v_pk_fma_f32 v[16:17], v[0:1], v[10:11], v[16:17]
	v_add_f32_e32 v18, 1.0, v18
	v_add_f32_e32 v19, 1.0, v19
	v_rcp_f32_e32 v18, v18
	v_rcp_f32_e32 v19, v19
	s_nop 0
	v_pk_mul_f32 v[12:13], v[12:13], v[18:19]
	s_nop 0
	v_cvt_pk_bf16_f32 v12, v12, v13
	v_add_u32_e32 v13, 0x9600, v2
	ds_write2_b32 v13, v3, v12 offset0:92 offset1:160
	s_waitcnt vmcnt(21)
	v_lshlrev_b32_e32 v12, 16, v59
	v_and_b32_e32 v13, 0xffff0000, v59
	v_pk_fma_f32 v[14:15], v[4:5], v[12:13], v[14:15]
	v_pk_fma_f32 v[16:17], v[8:9], v[12:13], v[16:17]
	v_mul_f32_e32 v3, 0xbfb8aa3b, v14
	v_exp_f32_e32 v3, v3
	s_nop 0
	v_add_f32_e32 v3, 1.0, v3
	v_rcp_f32_e32 v18, v3
	v_mul_f32_e32 v3, 0xbfb8aa3b, v15
	v_exp_f32_e32 v3, v3
	s_nop 0
	v_add_f32_e32 v3, 1.0, v3
	v_rcp_f32_e32 v19, v3
	s_nop 0
	v_pk_mul_f32 v[14:15], v[14:15], v[18:19]
	s_nop 0
	v_cvt_pk_bf16_f32 v3, v14, v15
	s_waitcnt vmcnt(20)
	v_lshlrev_b32_e32 v14, 16, v58
	v_and_b32_e32 v15, 0xffff0000, v58
	v_pk_fma_f32 v[16:17], v[4:5], v[14:15], v[16:17]
	s_nop 0
	v_mul_f32_e32 v18, 0xbfb8aa3b, v16
	v_mul_f32_e32 v19, 0xbfb8aa3b, v17
	v_exp_f32_e32 v18, v18
	v_exp_f32_e32 v19, v19
	v_add_f32_e32 v18, 1.0, v18
	v_add_f32_e32 v19, 1.0, v19
	v_rcp_f32_e32 v18, v18
	v_rcp_f32_e32 v19, v19
	s_nop 0
	v_pk_mul_f32 v[16:17], v[16:17], v[18:19]
	s_nop 0
	v_cvt_pk_bf16_f32 v16, v16, v17
	v_add_u32_e32 v17, 0x9800, v2
	ds_write2_b32 v17, v3, v16 offset0:100 offset1:168
	v_pk_fma_f32 v[10:11], v[6:7], v[10:11], 0 op_sel_hi:[1,1,0]
	s_waitcnt vmcnt(19)
	v_lshlrev_b32_e32 v16, 16, v57
	v_pk_fma_f32 v[10:11], v[0:1], v[12:13], v[10:11]
	v_and_b32_e32 v17, 0xffff0000, v57
	v_pk_fma_f32 v[10:11], v[8:9], v[14:15], v[10:11]
	v_pk_fma_f32 v[12:13], v[6:7], v[12:13], 0 op_sel_hi:[1,1,0]
	v_pk_fma_f32 v[10:11], v[4:5], v[16:17], v[10:11]
	v_pk_fma_f32 v[12:13], v[0:1], v[14:15], v[12:13]
	v_mul_f32_e32 v3, 0xbfb8aa3b, v10
	v_exp_f32_e32 v3, v3
	v_pk_fma_f32 v[12:13], v[8:9], v[16:17], v[12:13]
	v_pk_fma_f32 v[14:15], v[6:7], v[14:15], 0 op_sel_hi:[1,1,0]
	v_pk_fma_f32 v[6:7], v[6:7], v[16:17], 0 op_sel_hi:[1,1,0]
	v_add_f32_e32 v3, 1.0, v3
	v_rcp_f32_e32 v18, v3
	v_mul_f32_e32 v3, 0xbfb8aa3b, v11
	v_exp_f32_e32 v3, v3
	v_pk_fma_f32 v[14:15], v[0:1], v[16:17], v[14:15]
	v_add_f32_e32 v3, 1.0, v3
	v_rcp_f32_e32 v19, v3
	s_nop 0
	v_pk_mul_f32 v[10:11], v[10:11], v[18:19]
	s_nop 0
	v_cvt_pk_bf16_f32 v3, v10, v11
	s_waitcnt vmcnt(18)
	v_lshlrev_b32_e32 v10, 16, v56
	v_and_b32_e32 v11, 0xffff0000, v56
	v_pk_fma_f32 v[12:13], v[4:5], v[10:11], v[12:13]
	v_pk_fma_f32 v[14:15], v[8:9], v[10:11], v[14:15]
	v_mul_f32_e32 v18, 0xbfb8aa3b, v12
	v_mul_f32_e32 v19, 0xbfb8aa3b, v13
	v_exp_f32_e32 v18, v18
	v_exp_f32_e32 v19, v19
	v_pk_fma_f32 v[0:1], v[0:1], v[10:11], v[6:7]
	v_add_f32_e32 v18, 1.0, v18
	v_add_f32_e32 v19, 1.0, v19
	v_rcp_f32_e32 v18, v18
	v_rcp_f32_e32 v19, v19
	s_nop 0
	v_pk_mul_f32 v[12:13], v[12:13], v[18:19]
	s_nop 0
	v_cvt_pk_bf16_f32 v12, v12, v13
	v_add_u32_e32 v13, 0x9a00, v2
	ds_write2_b32 v13, v3, v12 offset0:108 offset1:176
	s_waitcnt vmcnt(17)
	v_lshlrev_b32_e32 v12, 16, v55
	v_and_b32_e32 v13, 0xffff0000, v55
	v_pk_fma_f32 v[14:15], v[4:5], v[12:13], v[14:15]
	v_pk_fma_f32 v[0:1], v[8:9], v[12:13], v[0:1]
	v_mul_f32_e32 v3, 0xbfb8aa3b, v14
	v_exp_f32_e32 v3, v3
	s_nop 0
	v_add_f32_e32 v3, 1.0, v3
	v_rcp_f32_e32 v18, v3
	v_mul_f32_e32 v3, 0xbfb8aa3b, v15
	v_exp_f32_e32 v3, v3
	s_nop 0
	v_add_f32_e32 v3, 1.0, v3
	v_rcp_f32_e32 v19, v3
	s_nop 0
	v_pk_mul_f32 v[14:15], v[14:15], v[18:19]
	s_nop 0
	v_cvt_pk_bf16_f32 v3, v14, v15
	s_waitcnt vmcnt(16)
	v_lshlrev_b32_e32 v14, 16, v54
	v_and_b32_e32 v15, 0xffff0000, v54
	v_pk_fma_f32 v[0:1], v[4:5], v[14:15], v[0:1]
	s_nop 0
	v_mul_f32_e32 v4, 0xbfb8aa3b, v0
	v_mul_f32_e32 v5, 0xbfb8aa3b, v1
	v_exp_f32_e32 v4, v4
	v_exp_f32_e32 v5, v5
	v_add_f32_e32 v4, 1.0, v4
	v_add_f32_e32 v5, 1.0, v5
	v_rcp_f32_e32 v4, v4
	v_rcp_f32_e32 v5, v5
	s_nop 0
	v_pk_mul_f32 v[0:1], v[0:1], v[4:5]
	s_nop 0
	v_cvt_pk_bf16_f32 v0, v0, v1
	v_add_u32_e32 v1, 0x9c00, v2
	ds_write2_b32 v1, v3, v0 offset0:116 offset1:184
	s_add_i32 s10, 0, 0x1a000
	v_lshl_add_u32 v0, v50, 2, s10
	s_movk_i32 s0, 0x1040
	v_mad_u64_u32 v[2:3], s[6:7], v159, s0, v[0:1]
	s_movk_i32 s0, 0x104
	v_mad_u64_u32 v[0:1], s[6:7], v161, s0, v[0:1]
	v_add_u32_e32 v1, 0x400, v0
	s_waitcnt vmcnt(15)
	ds_write_b32 v2, v24
	s_waitcnt vmcnt(13)
	ds_write2_b32 v0, v20, v21 offset1:65
	s_waitcnt vmcnt(11)
	ds_write2_b32 v0, v22, v25 offset0:130 offset1:195
	s_waitcnt vmcnt(9)
	ds_write2_b32 v1, v23, v26 offset0:4 offset1:69
	s_waitcnt vmcnt(7)
	ds_write2_b32 v1, v27, v29 offset0:134 offset1:199
	v_add_u32_e32 v1, 0x800, v0
	s_waitcnt vmcnt(5)
	ds_write2_b32 v1, v28, v30 offset0:8 offset1:73
	s_waitcnt vmcnt(3)
	ds_write2_b32 v1, v31, v49 offset0:138 offset1:203
	v_add_u32_e32 v1, 0xc00, v0
	s_waitcnt vmcnt(1)
	ds_write2_b32 v1, v48, v52 offset0:12 offset1:77
	s_waitcnt vmcnt(0)
	ds_write_b32 v0, v53 offset:3640
	v_cmp_gt_i32_e32 vcc, s83, v64
	s_and_saveexec_b64 s[6:7], vcc
	s_cbranch_execz .LBB0_1171
	v_lshl_add_u32 v1, v64, 2, 0
	ds_write_b32 v1, v236 offset:1536

.LBB0_1307:
	s_mov_b64 s[8:9], s[62:63]
	s_load_dwordx2 s[14:15], s[8:9], 0xc0
	s_load_dwordx2 s[28:29], s[8:9], 0x38
	s_load_dwordx2 s[30:31], s[8:9], 0x28
	s_load_dwordx2 s[34:35], s[8:9], 0x30
	v_mov_b32_e32 v64, v208
	s_and_b32 s11, s25, 0xfffff800
	s_and_b32 s6, s24, 0x780
	s_lshr_b32 s7, s26, 4
	v_ashrrev_i32_e32 v202, 6, v64
	s_bfe_u32 s10, s26, 0x20004
	s_or_b32 s5, s11, s6
	v_lshlrev_b32_e32 v97, 4, v202
	s_lshl_b32 s27, s10, 7
	s_bfe_u32 s96, s7, 0x10001
	v_and_b32_e32 v50, 63, v64
	v_add_u32_e32 v74, s5, v97
	s_or_b32 s7, s96, 6
	v_mov_b32_e32 v6, s27
	v_lshlrev_b32_e32 v203, 1, v50
	s_movk_i32 s0, 0xfe
	v_ashrrev_i32_e32 v75, 31, v74
	s_or_b32 s8, s96, 8
	v_mov_b32_e32 v166, s7
	v_bitop3_b32 v8, v203, s0, v6 bitop3:0xc8
	v_lshlrev_b32_e32 v6, 8, v74
	v_alignbit_b32 v52, v75, v74, 8
	v_mov_b32_e32 v5, v167
	v_mov_b32_e32 v4, s8
	v_and_b32_e32 v9, 0xf000, v6
	v_mad_u64_u32 v[6:7], s[8:9], v52, 49, v[166:167]
	v_mad_u64_u32 v[4:5], s[8:9], v52, 49, v[4:5]
	v_mad_u32_u24 v7, v75, 49, v7
	s_mov_b64 s[2:3], 0x74c2800
	v_mad_u32_u24 v5, v75, 49, v5
	v_lshlrev_b64 v[6:7], 17, v[6:7]
	v_lshlrev_b32_e32 v166, 1, v8
	v_lshlrev_b64 v[4:5], 17, v[4:5]
	v_mov_b32_e32 v19, v167
	v_lshlrev_b32_e32 v18, 1, v9
	v_lshlrev_b32_e32 v51, 3, v64
	v_or_b32_e32 v204, s27, v203
	s_lshl_b64 s[8:9], s[18:19], 2
	v_mov_b64_e32 v[30:31], s[96:97]
	s_waitcnt lgkmcnt(0)
	v_mov_b32_e32 v76, s14
	v_mov_b32_e32 v77, s15
	v_mov_b32_e32 v78, s28
	v_mov_b32_e32 v79, s29
	v_mov_b32_e32 v0, s30
	v_mov_b32_e32 v1, s31
	v_mov_b32_e32 v2, s34
	v_mov_b32_e32 v3, s35
	v_lshl_add_u64 v[20:21], v[76:77], 0, s[2:3]
	v_cmp_gt_i32_e32 vcc, 0x80, v208
	s_and_saveexec_b64 s[28:29], vcc
	v_add_u32_e32 v224, s5, v208
	v_ashrrev_i32_e32 v225, 31, v224
	v_lshlrev_b64 v[224:225], 5, v[224:225]
	v_lshl_add_u64 v[224:225], v[76:77], 0, v[224:225]
	s_lshl_b32 s14, s10, 2
	s_mov_b32 s15, 0
	v_lshl_add_u64 v[224:225], v[224:225], 0, s[14:15]
	s_mov_b64 s[30:31], 0x7300000
	s_or_b32 s14, s10, s36
	v_lshl_add_u64 v[226:227], v[224:225], 0, s[30:31]
	s_lshl_b64 s[14:15], s[14:15], 2
	v_lshl_add_u64 v[228:229], v[2:3], 0, s[14:15]
	global_load_dword v232, v[226:227], off offset:16
	s_nop 0
	global_load_dword v233, v[228:229], off offset:16
	v_add_co_u32_e32 v224, vcc, 0x7300000, v224
	s_nop 1
	v_addc_co_u32_e32 v225, vcc, 0, v225, vcc
	global_load_dword v234, v[224:225], off
	s_nop 0
	global_load_dword v235, v[228:229], off
	v_add_u32_e32 v224, s24, v208
	v_ashrrev_i32_e32 v225, 31, v224
	v_lshl_add_u64 v[224:225], v[224:225], 2, v[76:77]
	v_add_co_u32_e32 v224, vcc, 0x7382000, v224
	s_nop 1
	v_addc_co_u32_e32 v225, vcc, 0, v225, vcc
	global_load_dword v236, v[224:225], off
	s_mov_b64 exec, s[28:29]
	v_lshl_add_u64 v[6:7], v[20:21], 0, v[6:7]
	v_lshl_add_u64 v[4:5], v[20:21], 0, v[4:5]
	v_lshl_add_u64 v[6:7], v[6:7], 0, v[166:167]
	v_lshl_add_u64 v[4:5], v[4:5], 0, v[166:167]
	v_lshl_add_u64 v[6:7], v[6:7], 0, v[18:19]
	v_lshl_add_u64 v[4:5], v[4:5], 0, v[18:19]
	global_load_dword v201, v[6:7], off
	global_load_dword v199, v[6:7], off offset:512
	global_load_dword v197, v[6:7], off offset:1024
	global_load_dword v194, v[6:7], off offset:1536
	global_load_dword v192, v[6:7], off offset:2048
	global_load_dword v190, v[6:7], off offset:2560
	global_load_dword v188, v[6:7], off offset:3072
	global_load_dword v186, v[6:7], off offset:3584
	global_load_dword v200, v[4:5], off
	global_load_dword v198, v[4:5], off offset:512
	global_load_dword v196, v[4:5], off offset:1024
	global_load_dword v195, v[4:5], off offset:1536
	global_load_dword v193, v[4:5], off offset:2048
	global_load_dword v191, v[4:5], off offset:2560
	global_load_dword v189, v[4:5], off offset:3072
	global_load_dword v187, v[4:5], off offset:3584
	v_add_co_u32_e32 v6, vcc, s91, v6
	s_mov_b64 s[2:3], 0x800
	s_nop 0
	v_addc_co_u32_e32 v7, vcc, 0, v7, vcc
	v_add_co_u32_e32 v4, vcc, s91, v4
	v_add_u32_e32 v19, s6, v97
	s_nop 0
	v_addc_co_u32_e32 v5, vcc, 0, v5, vcc
	global_load_dword v184, v[6:7], off
	global_load_dword v182, v[6:7], off offset:512
	global_load_dword v180, v[6:7], off offset:1024
	global_load_dword v178, v[6:7], off offset:1536
	global_load_dword v176, v[6:7], off offset:2048
	global_load_dword v165, v[6:7], off offset:2560
	global_load_dword v163, v[6:7], off offset:3072
	global_load_dword v162, v[6:7], off offset:3584
	global_load_dword v185, v[4:5], off
	global_load_dword v183, v[4:5], off offset:512
	global_load_dword v181, v[4:5], off offset:1024
	global_load_dword v179, v[4:5], off offset:1536
	global_load_dword v177, v[4:5], off offset:2048
	global_load_dword v169, v[4:5], off offset:2560
	global_load_dword v164, v[4:5], off offset:3072
	global_load_dword v161, v[4:5], off offset:3584
	v_and_b32_e32 v4, 0xffffff80, v51
	v_ashrrev_i32_e32 v5, 31, v4
	v_lshlrev_b32_e32 v6, 4, v64
	v_add_u32_e32 v8, 0x1000, v4
	v_and_b32_e32 v10, 0xf0, v6
	v_lshlrev_b64 v[6:7], 1, v[4:5]
	v_ashrrev_i32_e32 v9, 31, v8
	v_or_b32_e32 v6, v6, v10
	v_lshlrev_b64 v[8:9], 1, v[8:9]
	v_lshl_add_u64 v[6:7], v[76:77], 0, v[6:7]
	v_or_b32_e32 v8, v8, v10
	v_lshl_add_u64 v[6:7], v[6:7], 0, s[12:13]
	v_lshl_add_u64 v[8:9], v[76:77], 0, v[8:9]
	v_lshl_add_u64 v[8:9], v[8:9], 0, s[12:13]
	global_load_dwordx4 v[36:39], v[6:7], off
	global_load_dwordx4 v[32:35], v[8:9], off
	v_add_u32_e32 v6, 0x2000, v4
	v_add_u32_e32 v4, 0x3000, v4
	v_ashrrev_i32_e32 v7, 31, v6
	v_ashrrev_i32_e32 v5, 31, v4
	v_lshlrev_b64 v[6:7], 1, v[6:7]
	v_lshlrev_b64 v[4:5], 1, v[4:5]
	v_or_b32_e32 v6, v6, v10
	v_or_b32_e32 v4, v4, v10
	v_lshl_add_u64 v[6:7], v[76:77], 0, v[6:7]
	v_lshl_add_u64 v[4:5], v[76:77], 0, v[4:5]
	v_lshl_add_u64 v[6:7], v[6:7], 0, s[12:13]
	v_lshl_add_u64 v[4:5], v[4:5], 0, s[12:13]
	global_load_dwordx4 v[44:47], v[6:7], off
	global_load_dwordx4 v[40:43], v[4:5], off
	v_lshlrev_b32_e32 v4, 2, v204
	v_mov_b32_e32 v5, v167
	s_waitcnt vmcnt(41)
	v_lshl_add_u64 v[0:1], v[0:1], 0, v[4:5]
	v_lshl_add_u64 v[4:5], v[0:1], 0, s[2:3]
	v_lshl_add_u64 v[8:9], v[0:1], 0, s[8:9]
	v_lshl_add_u64 v[14:15], v[4:5], 0, s[8:9]
	s_lshl_b64 s[8:9], s[20:21], 2
	v_lshl_add_u64 v[16:17], v[0:1], 0, s[8:9]
	v_lshl_add_u64 v[22:23], v[4:5], 0, s[8:9]
	s_lshl_b64 s[8:9], s[22:23], 2
	v_lshl_add_u64 v[6:7], s[16:17], 2, v[0:1]
	v_lshl_add_u64 v[4:5], v[4:5], 0, s[8:9]
	v_lshl_add_u64 v[24:25], v[0:1], 0, s[8:9]
	global_load_dwordx2 v[10:11], v[6:7], off
	global_load_dwordx2 v[12:13], v[8:9], off
	global_load_dwordx2 v[0:1], v[14:15], off
	s_nop 0
	global_load_dwordx2 v[6:7], v[6:7], off offset:2048
	s_nop 0
	global_load_dwordx2 v[16:17], v[16:17], off
	s_nop 0
	global_load_dwordx2 v[14:15], v[24:25], off
	s_nop 0
	global_load_dwordx2 v[4:5], v[4:5], off
	s_nop 0
	global_load_dwordx2 v[8:9], v[22:23], off
	v_cmp_gt_i32_e64 s[8:9], 3, v19
	s_and_saveexec_b64 s[6:7], s[8:9]
	s_xor_b64 s[6:7], exec, s[6:7]
	v_mov_b64_e32 v[30:31], s[96:97]
	s_or_saveexec_b64 s[6:7], s[6:7]
	v_add_u32_e32 v22, s11, v19
	v_ashrrev_i32_e32 v23, 31, v22
	v_lshl_add_u64 v[28:29], v[22:23], 0, -3
	v_lshl_add_u64 v[26:27], v[22:23], 0, -2
	v_lshl_add_u64 v[24:25], v[22:23], 0, -1
	v_mov_b32_e32 v102, 0
	v_alignbit_b32 v55, v29, v28, 8
	v_lshlrev_b32_e32 v54, 9, v28
	v_alignbit_b32 v53, v27, v26, 8
	v_lshlrev_b32_e32 v28, 9, v26
	v_alignbit_b32 v26, v25, v24, 8
	v_lshlrev_b32_e32 v19, 9, v24
	v_mov_b32_e32 v104, 0
	v_mov_b32_e32 v105, 0
	s_xor_b64 exec, exec, s[6:7]
	s_cbranch_execz .LBB0_1311
	v_mad_u64_u32 v[48:49], s[14:15], v55, 49, s[96:97]
	v_mad_u32_u24 v49, v29, 49, v49
	v_lshlrev_b64 v[48:49], 17, v[48:49]
	v_lshl_add_u64 v[48:49], v[20:21], 0, v[48:49]
	v_and_b32_e32 v56, 0x1fe00, v54
	v_mov_b32_e32 v57, v167
	v_lshl_add_u64 v[48:49], v[48:49], 0, v[56:57]
	v_lshl_add_u64 v[48:49], v[48:49], 0, v[166:167]
	global_load_dword v102, v[48:49], off
	v_mad_u64_u32 v[48:49], s[14:15], v53, 49, s[96:97]
	v_mad_u32_u24 v49, v27, 49, v49
	v_lshlrev_b64 v[48:49], 17, v[48:49]
	v_lshl_add_u64 v[48:49], v[20:21], 0, v[48:49]
	v_and_b32_e32 v56, 0x1fe00, v28
	v_lshl_add_u64 v[48:49], v[48:49], 0, v[56:57]
	v_lshl_add_u64 v[48:49], v[48:49], 0, v[166:167]
	global_load_dword v104, v[48:49], off
	v_mad_u64_u32 v[48:49], s[14:15], v26, 49, s[96:97]
	v_mad_u32_u24 v49, v25, 49, v49
	v_lshlrev_b64 v[48:49], 17, v[48:49]
	v_lshl_add_u64 v[48:49], v[20:21], 0, v[48:49]
	v_and_b32_e32 v56, 0x1fe00, v19
	v_lshl_add_u64 v[48:49], v[48:49], 0, v[56:57]
	v_lshl_add_u64 v[48:49], v[48:49], 0, v[166:167]
	global_load_dword v105, v[48:49], off

.LBB0_1323:
	s_or_b64 exec, exec, s[6:7]
	s_waitcnt lgkmcnt(0)
	s_barrier
	s_waitcnt vmcnt(50)
	v_lshlrev_b32_e32 v18, 16, v102
	v_and_b32_e32 v19, 0xffff0000, v102
	s_waitcnt vmcnt(47)
	v_lshlrev_b32_e32 v108, 16, v106
	v_and_b32_e32 v109, 0xffff0000, v106
	v_pk_fma_f32 v[18:19], v[10:11], v[18:19], 0 op_sel_hi:[1,1,0]
	v_lshlrev_b32_e32 v106, 16, v104
	v_and_b32_e32 v107, 0xffff0000, v104
	v_pk_fma_f32 v[18:19], v[12:13], v[106:107], v[18:19]
	v_lshlrev_b32_e32 v104, 16, v105
	v_and_b32_e32 v105, 0xffff0000, v105
	v_pk_fma_f32 v[18:19], v[16:17], v[104:105], v[18:19]
	s_mov_b32 s2, 0x3db504f3
	v_pk_fma_f32 v[18:19], v[14:15], v[108:109], v[18:19]
	v_pk_fma_f32 v[106:107], v[10:11], v[106:107], 0 op_sel_hi:[1,1,0]
	v_mul_f32_e32 v3, 0xbfb8aa3b, v18
	v_exp_f32_e32 v3, v3
	v_pk_fma_f32 v[106:107], v[12:13], v[104:105], v[106:107]
	v_lshl_add_u32 v2, v203, 1, 0
	s_movk_i32 s0, 0x1100
	v_add_f32_e32 v3, 1.0, v3
	v_rcp_f32_e32 v110, v3
	v_mul_f32_e32 v3, 0xbfb8aa3b, v19
	v_exp_f32_e32 v3, v3
	s_waitcnt vmcnt(46)
	v_lshlrev_b32_e32 v102, 16, v103
	v_and_b32_e32 v103, 0xffff0000, v103
	v_pk_fma_f32 v[106:107], v[16:17], v[108:109], v[106:107]
	v_add_f32_e32 v3, 1.0, v3
	v_rcp_f32_e32 v111, v3
	v_pk_fma_f32 v[106:107], v[14:15], v[102:103], v[106:107]
	v_pk_fma_f32 v[104:105], v[10:11], v[104:105], 0 op_sel_hi:[1,1,0]
	v_or_b32_e32 v205, 1, v97
	v_pk_mul_f32 v[18:19], v[18:19], v[110:111]
	v_pk_fma_f32 v[104:105], v[12:13], v[108:109], v[104:105]
	v_pk_mul_f32 v[18:19], v[18:19], s[2:3] op_sel_hi:[1,0]
	v_pk_fma_f32 v[104:105], v[16:17], v[102:103], v[104:105]
	v_cvt_pk_bf16_f32 v3, v18, v19
	v_mad_u64_u32 v[18:19], s[6:7], v202, s0, v[2:3]
	ds_write_b32 v18, v3 offset:2048
	v_mul_f32_e32 v3, 0xbfb8aa3b, v106
	v_exp_f32_e32 v3, v3
	s_nop 0
	v_add_f32_e32 v3, 1.0, v3
	v_rcp_f32_e32 v110, v3
	v_mul_f32_e32 v3, 0xbfb8aa3b, v107
	v_exp_f32_e32 v3, v3
	s_nop 0
	v_add_f32_e32 v3, 1.0, v3
	v_rcp_f32_e32 v111, v3
	v_mad_u64_u32 v[2:3], s[6:7], v205, s50, v[2:3]
	v_add_u32_e32 v97, 0x800, v2
	v_pk_mul_f32 v[106:107], v[106:107], v[110:111]
	s_nop 0
	v_pk_mul_f32 v[106:107], v[106:107], s[2:3] op_sel_hi:[1,0]
	s_nop 0
	v_cvt_pk_bf16_f32 v19, v106, v107
	s_waitcnt vmcnt(45)
	v_lshlrev_b32_e32 v106, 16, v101
	v_and_b32_e32 v107, 0xffff0000, v101
	v_pk_fma_f32 v[104:105], v[14:15], v[106:107], v[104:105]
	s_nop 0
	v_mul_f32_e32 v3, 0xbfb8aa3b, v104
	v_exp_f32_e32 v3, v3
	s_nop 0
	v_add_f32_e32 v3, 1.0, v3
	v_rcp_f32_e32 v110, v3
	v_mul_f32_e32 v3, 0xbfb8aa3b, v105
	v_exp_f32_e32 v3, v3
	s_nop 0
	v_add_f32_e32 v3, 1.0, v3
	v_rcp_f32_e32 v111, v3
	s_nop 0
	v_pk_mul_f32 v[104:105], v[104:105], v[110:111]
	s_nop 0
	v_pk_mul_f32 v[104:105], v[104:105], s[2:3] op_sel_hi:[1,0]
	s_nop 0
	v_cvt_pk_bf16_f32 v3, v104, v105
	s_waitcnt vmcnt(44)
	v_lshlrev_b32_e32 v104, 16, v100
	v_and_b32_e32 v105, 0xffff0000, v100
	v_pk_fma_f32 v[100:101], v[10:11], v[108:109], 0 op_sel_hi:[1,1,0]
	ds_write2_b32 v97, v19, v3 offset1:68
	v_pk_fma_f32 v[100:101], v[12:13], v[102:103], v[100:101]
	s_nop 0
	v_pk_fma_f32 v[100:101], v[16:17], v[106:107], v[100:101]
	s_nop 0
	v_pk_fma_f32 v[100:101], v[14:15], v[104:105], v[100:101]
	s_nop 0
	v_mul_f32_e32 v3, 0xbfb8aa3b, v100
	v_exp_f32_e32 v3, v3
	s_nop 0
	v_add_f32_e32 v3, 1.0, v3
	v_rcp_f32_e32 v108, v3
	v_mul_f32_e32 v3, 0xbfb8aa3b, v101
	v_exp_f32_e32 v3, v3
	s_nop 0
	v_add_f32_e32 v3, 1.0, v3
	v_rcp_f32_e32 v109, v3
	s_nop 0
	v_pk_mul_f32 v[100:101], v[100:101], v[108:109]
	s_nop 0
	v_pk_mul_f32 v[100:101], v[100:101], s[2:3] op_sel_hi:[1,0]
	s_nop 0
	v_cvt_pk_bf16_f32 v3, v100, v101
	ds_write_b32 v2, v3 offset:2592
	v_pk_fma_f32 v[102:103], v[10:11], v[102:103], 0 op_sel_hi:[1,1,0]
	s_waitcnt vmcnt(43)
	v_lshlrev_b32_e32 v100, 16, v99
	v_pk_fma_f32 v[102:103], v[12:13], v[106:107], v[102:103]
	v_and_b32_e32 v101, 0xffff0000, v99
	v_pk_fma_f32 v[102:103], v[16:17], v[104:105], v[102:103]
	v_add_u32_e32 v97, 0xa00, v2
	v_pk_fma_f32 v[102:103], v[14:15], v[100:101], v[102:103]
	s_nop 0
	v_mul_f32_e32 v3, 0xbfb8aa3b, v102
	v_exp_f32_e32 v3, v3
	s_nop 0
	v_add_f32_e32 v3, 1.0, v3
	v_rcp_f32_e32 v108, v3
	v_mul_f32_e32 v3, 0xbfb8aa3b, v103
	v_exp_f32_e32 v3, v3
	s_nop 0
	v_add_f32_e32 v3, 1.0, v3
	v_rcp_f32_e32 v109, v3
	s_nop 0
	v_pk_mul_f32 v[102:103], v[102:103], v[108:109]
	s_nop 0
	v_pk_mul_f32 v[102:103], v[102:103], s[2:3] op_sel_hi:[1,0]
	s_nop 0
	v_cvt_pk_bf16_f32 v3, v102, v103
	s_waitcnt vmcnt(42)
	v_lshlrev_b32_e32 v102, 16, v98
	v_and_b32_e32 v103, 0xffff0000, v98
	v_pk_fma_f32 v[98:99], v[10:11], v[106:107], 0 op_sel_hi:[1,1,0]
	s_nop 0
	v_pk_fma_f32 v[98:99], v[12:13], v[104:105], v[98:99]
	s_nop 0
	v_pk_fma_f32 v[98:99], v[16:17], v[100:101], v[98:99]
	s_nop 0
	v_pk_fma_f32 v[98:99], v[14:15], v[102:103], v[98:99]
	s_nop 0
	v_mul_f32_e32 v19, 0xbfb8aa3b, v98
	v_exp_f32_e32 v19, v19
	s_nop 0
	v_add_f32_e32 v19, 1.0, v19
	v_rcp_f32_e32 v106, v19
	v_mul_f32_e32 v19, 0xbfb8aa3b, v99
	v_exp_f32_e32 v19, v19
	s_nop 0
	v_add_f32_e32 v19, 1.0, v19
	v_rcp_f32_e32 v107, v19
	s_nop 0
	v_pk_mul_f32 v[98:99], v[98:99], v[106:107]
	s_nop 0
	v_pk_mul_f32 v[98:99], v[98:99], s[2:3] op_sel_hi:[1,0]
	s_nop 0
	v_cvt_pk_bf16_f32 v19, v98, v99
	ds_write2_b32 v97, v3, v19 offset0:76 offset1:144
	s_waitcnt vmcnt(41)
	v_lshlrev_b32_e32 v98, 16, v96
	v_and_b32_e32 v99, 0xffff0000, v96
	v_pk_fma_f32 v[96:97], v[10:11], v[104:105], 0 op_sel_hi:[1,1,0]
	s_nop 0
	v_pk_fma_f32 v[96:97], v[12:13], v[100:101], v[96:97]
	v_pk_fma_f32 v[100:101], v[10:11], v[100:101], 0 op_sel_hi:[1,1,0]
	v_pk_fma_f32 v[96:97], v[16:17], v[102:103], v[96:97]
	v_pk_fma_f32 v[100:101], v[12:13], v[102:103], v[100:101]
	v_pk_fma_f32 v[96:97], v[14:15], v[98:99], v[96:97]
	v_pk_fma_f32 v[100:101], v[16:17], v[98:99], v[100:101]
	v_mul_f32_e32 v3, 0xbfb8aa3b, v96
	v_exp_f32_e32 v3, v3
	s_nop 0
	v_add_f32_e32 v3, 1.0, v3
	v_rcp_f32_e32 v104, v3
	v_mul_f32_e32 v3, 0xbfb8aa3b, v97
	v_exp_f32_e32 v3, v3
	s_nop 0
	v_add_f32_e32 v3, 1.0, v3
	v_rcp_f32_e32 v105, v3
	s_nop 0
	v_pk_mul_f32 v[96:97], v[96:97], v[104:105]
	s_nop 0
	v_pk_mul_f32 v[96:97], v[96:97], s[2:3] op_sel_hi:[1,0]
	s_nop 0
	v_cvt_pk_bf16_f32 v3, v96, v97
	s_waitcnt vmcnt(40)
	v_lshlrev_b32_e32 v96, 16, v95
	v_and_b32_e32 v97, 0xffff0000, v95
	v_pk_fma_f32 v[100:101], v[14:15], v[96:97], v[100:101]
	v_add_u32_e32 v95, 0xc00, v2
	v_mul_f32_e32 v19, 0xbfb8aa3b, v100
	v_exp_f32_e32 v19, v19
	s_nop 0
	v_add_f32_e32 v19, 1.0, v19
	v_rcp_f32_e32 v104, v19
	v_mul_f32_e32 v19, 0xbfb8aa3b, v101
	v_exp_f32_e32 v19, v19
	s_nop 0
	v_add_f32_e32 v19, 1.0, v19
	v_rcp_f32_e32 v105, v19
	s_nop 0
	v_pk_mul_f32 v[100:101], v[100:101], v[104:105]
	s_nop 0
	v_pk_mul_f32 v[100:101], v[100:101], s[2:3] op_sel_hi:[1,0]
	s_nop 0
	v_cvt_pk_bf16_f32 v19, v100, v101
	ds_write2_b32 v95, v3, v19 offset0:84 offset1:152
	s_waitcnt vmcnt(39)
	v_lshlrev_b32_e32 v100, 16, v94
	v_and_b32_e32 v101, 0xffff0000, v94
	v_pk_fma_f32 v[94:95], v[10:11], v[102:103], 0 op_sel_hi:[1,1,0]
	s_nop 0
	v_pk_fma_f32 v[94:95], v[12:13], v[98:99], v[94:95]
	v_pk_fma_f32 v[98:99], v[10:11], v[98:99], 0 op_sel_hi:[1,1,0]
	v_pk_fma_f32 v[94:95], v[16:17], v[96:97], v[94:95]
	v_pk_fma_f32 v[98:99], v[12:13], v[96:97], v[98:99]
	v_pk_fma_f32 v[94:95], v[14:15], v[100:101], v[94:95]
	v_pk_fma_f32 v[98:99], v[16:17], v[100:101], v[98:99]
	v_mul_f32_e32 v3, 0xbfb8aa3b, v94
	v_exp_f32_e32 v3, v3
	s_nop 0
	v_add_f32_e32 v3, 1.0, v3
	v_rcp_f32_e32 v102, v3
	v_mul_f32_e32 v3, 0xbfb8aa3b, v95
	v_exp_f32_e32 v3, v3
	s_nop 0
	v_add_f32_e32 v3, 1.0, v3
	v_rcp_f32_e32 v103, v3
	s_nop 0
	v_pk_mul_f32 v[94:95], v[94:95], v[102:103]
	s_nop 0
	v_pk_mul_f32 v[94:95], v[94:95], s[2:3] op_sel_hi:[1,0]
	s_nop 0
	v_cvt_pk_bf16_f32 v3, v94, v95
	s_waitcnt vmcnt(38)
	v_lshlrev_b32_e32 v94, 16, v93
	v_and_b32_e32 v95, 0xffff0000, v93
	v_pk_fma_f32 v[98:99], v[14:15], v[94:95], v[98:99]
	v_add_u32_e32 v93, 0xe00, v2
	v_mul_f32_e32 v19, 0xbfb8aa3b, v98
	v_exp_f32_e32 v19, v19
	s_nop 0
	v_add_f32_e32 v19, 1.0, v19
	v_rcp_f32_e32 v102, v19
	v_mul_f32_e32 v19, 0xbfb8aa3b, v99
	v_exp_f32_e32 v19, v19
	s_nop 0
	v_add_f32_e32 v19, 1.0, v19
	v_rcp_f32_e32 v103, v19
	s_nop 0
	v_pk_mul_f32 v[98:99], v[98:99], v[102:103]
	s_nop 0
	v_pk_mul_f32 v[98:99], v[98:99], s[2:3] op_sel_hi:[1,0]
	s_nop 0
	v_cvt_pk_bf16_f32 v19, v98, v99
	ds_write2_b32 v93, v3, v19 offset0:92 offset1:160
	s_waitcnt vmcnt(37)
	v_lshlrev_b32_e32 v98, 16, v92
	v_and_b32_e32 v99, 0xffff0000, v92
	v_pk_fma_f32 v[92:93], v[10:11], v[96:97], 0 op_sel_hi:[1,1,0]
	s_nop 0
	v_pk_fma_f32 v[92:93], v[12:13], v[100:101], v[92:93]
	s_nop 0
	v_pk_fma_f32 v[92:93], v[16:17], v[94:95], v[92:93]
	s_nop 0
	v_pk_fma_f32 v[92:93], v[14:15], v[98:99], v[92:93]
	s_nop 0
	v_mul_f32_e32 v3, 0xbfb8aa3b, v92
	v_exp_f32_e32 v3, v3
	s_nop 0
	v_add_f32_e32 v3, 1.0, v3
	v_rcp_f32_e32 v96, v3
	v_mul_f32_e32 v3, 0xbfb8aa3b, v93
	v_exp_f32_e32 v3, v3
	s_nop 0
	v_add_f32_e32 v3, 1.0, v3
	v_rcp_f32_e32 v97, v3
	s_nop 0
	v_pk_mul_f32 v[92:93], v[92:93], v[96:97]
	v_pk_fma_f32 v[96:97], v[10:11], v[100:101], 0 op_sel_hi:[1,1,0]
	v_pk_mul_f32 v[92:93], v[92:93], s[2:3] op_sel_hi:[1,0]
	v_pk_fma_f32 v[96:97], v[12:13], v[94:95], v[96:97]
	v_cvt_pk_bf16_f32 v3, v92, v93
	s_waitcnt vmcnt(36)
	v_lshlrev_b32_e32 v92, 16, v91
	v_and_b32_e32 v93, 0xffff0000, v91
	v_pk_fma_f32 v[96:97], v[16:17], v[98:99], v[96:97]
	v_add_u32_e32 v91, 0x1000, v2
	v_pk_fma_f32 v[96:97], v[14:15], v[92:93], v[96:97]
	s_nop 0
	v_mul_f32_e32 v19, 0xbfb8aa3b, v96
	v_exp_f32_e32 v19, v19
	s_nop 0
	v_add_f32_e32 v19, 1.0, v19
	v_rcp_f32_e32 v100, v19
	v_mul_f32_e32 v19, 0xbfb8aa3b, v97
	v_exp_f32_e32 v19, v19
	s_nop 0
	v_add_f32_e32 v19, 1.0, v19
	v_rcp_f32_e32 v101, v19
	s_nop 0
	v_pk_mul_f32 v[96:97], v[96:97], v[100:101]
	s_nop 0
	v_pk_mul_f32 v[96:97], v[96:97], s[2:3] op_sel_hi:[1,0]
	s_nop 0
	v_cvt_pk_bf16_f32 v19, v96, v97
	ds_write2_b32 v91, v3, v19 offset0:100 offset1:168
	s_waitcnt vmcnt(35)
	v_lshlrev_b32_e32 v96, 16, v90
	v_and_b32_e32 v97, 0xffff0000, v90
	v_pk_fma_f32 v[90:91], v[10:11], v[94:95], 0 op_sel_hi:[1,1,0]
	s_nop 0
	v_pk_fma_f32 v[90:91], v[12:13], v[98:99], v[90:91]
	s_nop 0
	v_pk_fma_f32 v[90:91], v[16:17], v[92:93], v[90:91]
	s_nop 0
	v_pk_fma_f32 v[90:91], v[14:15], v[96:97], v[90:91]
	s_nop 0
	v_mul_f32_e32 v3, 0xbfb8aa3b, v90
	v_exp_f32_e32 v3, v3
	s_nop 0
	v_add_f32_e32 v3, 1.0, v3
	v_rcp_f32_e32 v94, v3
	v_mul_f32_e32 v3, 0xbfb8aa3b, v91
	v_exp_f32_e32 v3, v3
	s_nop 0
	v_add_f32_e32 v3, 1.0, v3
	v_rcp_f32_e32 v95, v3
	s_nop 0
	v_pk_mul_f32 v[90:91], v[90:91], v[94:95]
	v_pk_fma_f32 v[94:95], v[10:11], v[98:99], 0 op_sel_hi:[1,1,0]
	v_pk_mul_f32 v[90:91], v[90:91], s[2:3] op_sel_hi:[1,0]
	v_pk_fma_f32 v[94:95], v[12:13], v[92:93], v[94:95]
	v_cvt_pk_bf16_f32 v3, v90, v91
	s_waitcnt vmcnt(34)
	v_lshlrev_b32_e32 v90, 16, v89
	v_and_b32_e32 v91, 0xffff0000, v89
	v_pk_fma_f32 v[94:95], v[16:17], v[96:97], v[94:95]
	v_pk_fma_f32 v[92:93], v[10:11], v[92:93], 0 op_sel_hi:[1,1,0]
	v_pk_fma_f32 v[94:95], v[14:15], v[90:91], v[94:95]
	v_pk_fma_f32 v[92:93], v[12:13], v[96:97], v[92:93]
	v_mul_f32_e32 v19, 0xbfb8aa3b, v94
	v_exp_f32_e32 v19, v19
	v_pk_fma_f32 v[92:93], v[16:17], v[90:91], v[92:93]
	v_add_u32_e32 v89, 0x1200, v2
	v_pk_fma_f32 v[10:11], v[10:11], v[96:97], 0 op_sel_hi:[1,1,0]
	v_add_f32_e32 v19, 1.0, v19
	v_rcp_f32_e32 v98, v19
	v_mul_f32_e32 v19, 0xbfb8aa3b, v95
	v_exp_f32_e32 v19, v19
	v_pk_fma_f32 v[10:11], v[12:13], v[90:91], v[10:11]
	v_add_f32_e32 v19, 1.0, v19
	v_rcp_f32_e32 v99, v19
	s_nop 0
	v_pk_mul_f32 v[94:95], v[94:95], v[98:99]
	s_nop 0
	v_pk_mul_f32 v[94:95], v[94:95], s[2:3] op_sel_hi:[1,0]
	s_nop 0
	v_cvt_pk_bf16_f32 v19, v94, v95
	s_waitcnt vmcnt(33)
	v_lshlrev_b32_e32 v94, 16, v87
	v_and_b32_e32 v95, 0xffff0000, v87
	v_pk_fma_f32 v[92:93], v[14:15], v[94:95], v[92:93]
	ds_write2_b32 v89, v3, v19 offset0:108 offset1:176
	v_mul_f32_e32 v3, 0xbfb8aa3b, v92
	v_exp_f32_e32 v3, v3
	v_pk_fma_f32 v[10:11], v[16:17], v[94:95], v[10:11]
	v_add_f32_e32 v3, 1.0, v3
	v_rcp_f32_e32 v98, v3
	v_mul_f32_e32 v3, 0xbfb8aa3b, v93
	v_exp_f32_e32 v3, v3
	s_nop 0
	v_add_f32_e32 v3, 1.0, v3
	v_rcp_f32_e32 v99, v3
	s_nop 0
	v_pk_mul_f32 v[92:93], v[92:93], v[98:99]
	s_nop 0
	v_pk_mul_f32 v[92:93], v[92:93], s[2:3] op_sel_hi:[1,0]
	s_nop 0
	v_cvt_pk_bf16_f32 v3, v92, v93
	s_waitcnt vmcnt(32)
	v_lshlrev_b32_e32 v92, 16, v69
	v_and_b32_e32 v93, 0xffff0000, v69
	v_pk_fma_f32 v[10:11], v[14:15], v[92:93], v[10:11]
	s_nop 0
	v_mul_f32_e32 v12, 0xbfb8aa3b, v10
	v_mul_f32_e32 v13, 0xbfb8aa3b, v11
	v_exp_f32_e32 v12, v12
	v_exp_f32_e32 v13, v13
	v_add_f32_e32 v12, 1.0, v12
	v_add_f32_e32 v13, 1.0, v13
	v_rcp_f32_e32 v12, v12
	v_rcp_f32_e32 v13, v13
	s_nop 0
	v_pk_mul_f32 v[10:11], v[10:11], v[12:13]
	s_nop 0
	v_pk_mul_f32 v[10:11], v[10:11], s[2:3] op_sel_hi:[1,0]
	s_nop 0
	v_cvt_pk_bf16_f32 v10, v10, v11
	v_add_u32_e32 v11, 0x1400, v2
	ds_write2_b32 v11, v3, v10 offset0:116 offset1:184
	v_lshlrev_b32_e32 v10, 16, v71
	v_and_b32_e32 v11, 0xffff0000, v71
	v_lshlrev_b32_e32 v12, 16, v84
	v_and_b32_e32 v13, 0xffff0000, v84
	v_pk_fma_f32 v[10:11], v[6:7], v[10:11], 0 op_sel_hi:[1,1,0]
	v_lshlrev_b32_e32 v14, 16, v86
	v_and_b32_e32 v15, 0xffff0000, v86
	v_pk_fma_f32 v[10:11], v[0:1], v[12:13], v[10:11]
	s_waitcnt vmcnt(31)
	v_lshlrev_b32_e32 v16, 16, v88
	v_and_b32_e32 v17, 0xffff0000, v88
	v_pk_fma_f32 v[10:11], v[8:9], v[14:15], v[10:11]
	v_pk_fma_f32 v[12:13], v[6:7], v[12:13], 0 op_sel_hi:[1,1,0]
	v_pk_fma_f32 v[10:11], v[4:5], v[16:17], v[10:11]
	v_pk_fma_f32 v[12:13], v[0:1], v[14:15], v[12:13]
	v_mul_f32_e32 v3, 0xbfb8aa3b, v10
	v_exp_f32_e32 v3, v3
	v_pk_fma_f32 v[12:13], v[8:9], v[16:17], v[12:13]
	v_pk_fma_f32 v[14:15], v[6:7], v[14:15], 0 op_sel_hi:[1,1,0]
	v_add_f32_e32 v3, 1.0, v3
	v_rcp_f32_e32 v86, v3
	v_mul_f32_e32 v3, 0xbfb8aa3b, v11
	v_exp_f32_e32 v3, v3
	v_pk_fma_f32 v[14:15], v[0:1], v[16:17], v[14:15]
	v_pk_fma_f32 v[16:17], v[6:7], v[16:17], 0 op_sel_hi:[1,1,0]
	v_add_f32_e32 v3, 1.0, v3
	v_rcp_f32_e32 v87, v3
	s_nop 0
	v_pk_mul_f32 v[10:11], v[10:11], v[86:87]
	s_nop 0
	v_cvt_pk_bf16_f32 v3, v10, v11
	s_waitcnt vmcnt(30)
	v_lshlrev_b32_e32 v10, 16, v70
	v_and_b32_e32 v11, 0xffff0000, v70
	v_pk_fma_f32 v[12:13], v[4:5], v[10:11], v[12:13]
	ds_write_b32 v18, v3 offset:36864
	v_mul_f32_e32 v3, 0xbfb8aa3b, v12
	v_exp_f32_e32 v3, v3
	v_pk_fma_f32 v[14:15], v[8:9], v[10:11], v[14:15]
	v_pk_fma_f32 v[16:17], v[0:1], v[10:11], v[16:17]
	v_add_f32_e32 v3, 1.0, v3
	v_rcp_f32_e32 v18, v3
	v_mul_f32_e32 v3, 0xbfb8aa3b, v13
	v_exp_f32_e32 v3, v3
	s_nop 0
	v_add_f32_e32 v3, 1.0, v3
	v_rcp_f32_e32 v19, v3
	s_nop 0
	v_pk_mul_f32 v[12:13], v[12:13], v[18:19]
	s_nop 0
	v_cvt_pk_bf16_f32 v3, v12, v13
	s_waitcnt vmcnt(29)
	v_lshlrev_b32_e32 v12, 16, v68
	v_and_b32_e32 v13, 0xffff0000, v68
	v_pk_fma_f32 v[14:15], v[4:5], v[12:13], v[14:15]
	v_pk_fma_f32 v[16:17], v[8:9], v[12:13], v[16:17]
	v_mul_f32_e32 v18, 0xbfb8aa3b, v14
	v_mul_f32_e32 v19, 0xbfb8aa3b, v15
	v_exp_f32_e32 v18, v18
	v_exp_f32_e32 v19, v19
	v_add_f32_e32 v18, 1.0, v18
	v_add_f32_e32 v19, 1.0, v19
	v_rcp_f32_e32 v18, v18
	v_rcp_f32_e32 v19, v19
	s_nop 0
	v_pk_mul_f32 v[14:15], v[14:15], v[18:19]
	s_nop 0
	v_cvt_pk_bf16_f32 v14, v14, v15
	v_add_u32_e32 v15, 0x9000, v2
	ds_write2_b32 v15, v3, v14 offset1:68
	s_waitcnt vmcnt(28)
	v_lshlrev_b32_e32 v14, 16, v67
	v_and_b32_e32 v15, 0xffff0000, v67
	v_pk_fma_f32 v[16:17], v[4:5], v[14:15], v[16:17]
	s_nop 0
	v_mul_f32_e32 v3, 0xbfb8aa3b, v16
	v_exp_f32_e32 v3, v3
	s_nop 0
	v_add_f32_e32 v3, 1.0, v3
	v_rcp_f32_e32 v18, v3
	v_mul_f32_e32 v3, 0xbfb8aa3b, v17
	v_exp_f32_e32 v3, v3
	s_nop 0
	v_add_f32_e32 v3, 1.0, v3
	v_rcp_f32_e32 v19, v3
	s_nop 0
	v_pk_mul_f32 v[16:17], v[16:17], v[18:19]
	s_nop 0
	v_cvt_pk_bf16_f32 v3, v16, v17
	ds_write_b32 v2, v3 offset:37408
	v_pk_fma_f32 v[10:11], v[6:7], v[10:11], 0 op_sel_hi:[1,1,0]
	s_waitcnt vmcnt(27)
	v_lshlrev_b32_e32 v16, 16, v66
	v_pk_fma_f32 v[10:11], v[0:1], v[12:13], v[10:11]
	v_and_b32_e32 v17, 0xffff0000, v66
	v_pk_fma_f32 v[10:11], v[8:9], v[14:15], v[10:11]
	v_pk_fma_f32 v[12:13], v[6:7], v[12:13], 0 op_sel_hi:[1,1,0]
	v_pk_fma_f32 v[10:11], v[4:5], v[16:17], v[10:11]
	v_pk_fma_f32 v[12:13], v[0:1], v[14:15], v[12:13]
	v_mul_f32_e32 v3, 0xbfb8aa3b, v10
	v_exp_f32_e32 v3, v3
	v_pk_fma_f32 v[12:13], v[8:9], v[16:17], v[12:13]
	v_pk_fma_f32 v[14:15], v[6:7], v[14:15], 0 op_sel_hi:[1,1,0]
	v_add_f32_e32 v3, 1.0, v3
	v_rcp_f32_e32 v18, v3
	v_mul_f32_e32 v3, 0xbfb8aa3b, v11
	v_exp_f32_e32 v3, v3
	v_pk_fma_f32 v[14:15], v[0:1], v[16:17], v[14:15]
	v_pk_fma_f32 v[16:17], v[6:7], v[16:17], 0 op_sel_hi:[1,1,0]
	v_add_f32_e32 v3, 1.0, v3
	v_rcp_f32_e32 v19, v3
	s_nop 0
	v_pk_mul_f32 v[10:11], v[10:11], v[18:19]
	s_nop 0
	v_cvt_pk_bf16_f32 v3, v10, v11
	s_waitcnt vmcnt(26)
	v_lshlrev_b32_e32 v10, 16, v65
	v_and_b32_e32 v11, 0xffff0000, v65
	v_pk_fma_f32 v[12:13], v[4:5], v[10:11], v[12:13]
	v_pk_fma_f32 v[14:15], v[8:9], v[10:11], v[14:15]
	v_mul_f32_e32 v18, 0xbfb8aa3b, v12
	v_mul_f32_e32 v19, 0xbfb8aa3b, v13
	v_exp_f32_e32 v18, v18
	v_exp_f32_e32 v19, v19
	v_pk_fma_f32 v[16:17], v[0:1], v[10:11], v[16:17]
	v_add_f32_e32 v18, 1.0, v18
	v_add_f32_e32 v19, 1.0, v19
	v_rcp_f32_e32 v18, v18
	v_rcp_f32_e32 v19, v19
	s_nop 0
	v_pk_mul_f32 v[12:13], v[12:13], v[18:19]
	s_nop 0
	v_cvt_pk_bf16_f32 v12, v12, v13
	v_add_u32_e32 v13, 0x9200, v2
	ds_write2_b32 v13, v3, v12 offset0:76 offset1:144
	s_waitcnt vmcnt(25)
	v_lshlrev_b32_e32 v12, 16, v63
	v_and_b32_e32 v13, 0xffff0000, v63
	v_pk_fma_f32 v[14:15], v[4:5], v[12:13], v[14:15]
	v_pk_fma_f32 v[16:17], v[8:9], v[12:13], v[16:17]
	v_mul_f32_e32 v3, 0xbfb8aa3b, v14
	v_exp_f32_e32 v3, v3
	s_nop 0
	v_add_f32_e32 v3, 1.0, v3
	v_rcp_f32_e32 v18, v3
	v_mul_f32_e32 v3, 0xbfb8aa3b, v15
	v_exp_f32_e32 v3, v3
	s_nop 0
	v_add_f32_e32 v3, 1.0, v3
	v_rcp_f32_e32 v19, v3
	s_nop 0
	v_pk_mul_f32 v[14:15], v[14:15], v[18:19]
	s_nop 0
	v_cvt_pk_bf16_f32 v3, v14, v15
	s_waitcnt vmcnt(24)
	v_lshlrev_b32_e32 v14, 16, v62
	v_and_b32_e32 v15, 0xffff0000, v62
	v_pk_fma_f32 v[16:17], v[4:5], v[14:15], v[16:17]
	s_nop 0
	v_mul_f32_e32 v18, 0xbfb8aa3b, v16
	v_mul_f32_e32 v19, 0xbfb8aa3b, v17
	v_exp_f32_e32 v18, v18
	v_exp_f32_e32 v19, v19
	v_add_f32_e32 v18, 1.0, v18
	v_add_f32_e32 v19, 1.0, v19
	v_rcp_f32_e32 v18, v18
	v_rcp_f32_e32 v19, v19
	s_nop 0
	v_pk_mul_f32 v[16:17], v[16:17], v[18:19]
	s_nop 0
	v_cvt_pk_bf16_f32 v16, v16, v17
	v_add_u32_e32 v17, 0x9400, v2
	ds_write2_b32 v17, v3, v16 offset0:84 offset1:152
	v_pk_fma_f32 v[10:11], v[6:7], v[10:11], 0 op_sel_hi:[1,1,0]
	s_waitcnt vmcnt(23)
	v_lshlrev_b32_e32 v16, 16, v61
	v_pk_fma_f32 v[10:11], v[0:1], v[12:13], v[10:11]
	v_and_b32_e32 v17, 0xffff0000, v61
	v_pk_fma_f32 v[10:11], v[8:9], v[14:15], v[10:11]
	v_pk_fma_f32 v[12:13], v[6:7], v[12:13], 0 op_sel_hi:[1,1,0]
	v_pk_fma_f32 v[10:11], v[4:5], v[16:17], v[10:11]
	v_pk_fma_f32 v[12:13], v[0:1], v[14:15], v[12:13]
	v_mul_f32_e32 v3, 0xbfb8aa3b, v10
	v_exp_f32_e32 v3, v3
	v_pk_fma_f32 v[12:13], v[8:9], v[16:17], v[12:13]
	v_pk_fma_f32 v[14:15], v[6:7], v[14:15], 0 op_sel_hi:[1,1,0]
	v_add_f32_e32 v3, 1.0, v3
	v_rcp_f32_e32 v18, v3
	v_mul_f32_e32 v3, 0xbfb8aa3b, v11
	v_exp_f32_e32 v3, v3
	v_pk_fma_f32 v[14:15], v[0:1], v[16:17], v[14:15]
	v_pk_fma_f32 v[16:17], v[6:7], v[16:17], 0 op_sel_hi:[1,1,0]
	v_add_f32_e32 v3, 1.0, v3
	v_rcp_f32_e32 v19, v3
	s_nop 0
	v_pk_mul_f32 v[10:11], v[10:11], v[18:19]
	s_nop 0
	v_cvt_pk_bf16_f32 v3, v10, v11
	s_waitcnt vmcnt(22)
	v_lshlrev_b32_e32 v10, 16, v60
	v_and_b32_e32 v11, 0xffff0000, v60
	v_pk_fma_f32 v[12:13], v[4:5], v[10:11], v[12:13]
	v_pk_fma_f32 v[14:15], v[8:9], v[10:11], v[14:15]
	v_mul_f32_e32 v18, 0xbfb8aa3b, v12
	v_mul_f32_e32 v19, 0xbfb8aa3b, v13
	v_exp_f32_e32 v18, v18
	v_exp_f32_e32 v19, v19
	v_pk_fma_f32 v[16:17], v[0:1], v[10:11], v[16:17]
	v_add_f32_e32 v18, 1.0, v18
	v_add_f32_e32 v19, 1.0, v19
	v_rcp_f32_e32 v18, v18
	v_rcp_f32_e32 v19, v19
	s_nop 0
	v_pk_mul_f32 v[12:13], v[12:13], v[18:19]
	s_nop 0
	v_cvt_pk_bf16_f32 v12, v12, v13
	v_add_u32_e32 v13, 0x9600, v2
	ds_write2_b32 v13, v3, v12 offset0:92 offset1:160
	s_waitcnt vmcnt(21)
	v_lshlrev_b32_e32 v12, 16, v59
	v_and_b32_e32 v13, 0xffff0000, v59
	v_pk_fma_f32 v[14:15], v[4:5], v[12:13], v[14:15]
	v_pk_fma_f32 v[16:17], v[8:9], v[12:13], v[16:17]
	v_mul_f32_e32 v3, 0xbfb8aa3b, v14
	v_exp_f32_e32 v3, v3
	s_nop 0
	v_add_f32_e32 v3, 1.0, v3
	v_rcp_f32_e32 v18, v3
	v_mul_f32_e32 v3, 0xbfb8aa3b, v15
	v_exp_f32_e32 v3, v3
	s_nop 0
	v_add_f32_e32 v3, 1.0, v3
	v_rcp_f32_e32 v19, v3
	s_nop 0
	v_pk_mul_f32 v[14:15], v[14:15], v[18:19]
	s_nop 0
	v_cvt_pk_bf16_f32 v3, v14, v15
	s_waitcnt vmcnt(20)
	v_lshlrev_b32_e32 v14, 16, v58
	v_and_b32_e32 v15, 0xffff0000, v58
	v_pk_fma_f32 v[16:17], v[4:5], v[14:15], v[16:17]
	s_nop 0
	v_mul_f32_e32 v18, 0xbfb8aa3b, v16
	v_mul_f32_e32 v19, 0xbfb8aa3b, v17
	v_exp_f32_e32 v18, v18
	v_exp_f32_e32 v19, v19
	v_add_f32_e32 v18, 1.0, v18
	v_add_f32_e32 v19, 1.0, v19
	v_rcp_f32_e32 v18, v18
	v_rcp_f32_e32 v19, v19
	s_nop 0
	v_pk_mul_f32 v[16:17], v[16:17], v[18:19]
	s_nop 0
	v_cvt_pk_bf16_f32 v16, v16, v17
	v_add_u32_e32 v17, 0x9800, v2
	ds_write2_b32 v17, v3, v16 offset0:100 offset1:168
	v_pk_fma_f32 v[10:11], v[6:7], v[10:11], 0 op_sel_hi:[1,1,0]
	s_waitcnt vmcnt(19)
	v_lshlrev_b32_e32 v16, 16, v57
	v_pk_fma_f32 v[10:11], v[0:1], v[12:13], v[10:11]
	v_and_b32_e32 v17, 0xffff0000, v57
	v_pk_fma_f32 v[10:11], v[8:9], v[14:15], v[10:11]
	v_pk_fma_f32 v[12:13], v[6:7], v[12:13], 0 op_sel_hi:[1,1,0]
	v_pk_fma_f32 v[10:11], v[4:5], v[16:17], v[10:11]
	v_pk_fma_f32 v[12:13], v[0:1], v[14:15], v[12:13]
	v_mul_f32_e32 v3, 0xbfb8aa3b, v10
	v_exp_f32_e32 v3, v3
	v_pk_fma_f32 v[12:13], v[8:9], v[16:17], v[12:13]
	v_pk_fma_f32 v[14:15], v[6:7], v[14:15], 0 op_sel_hi:[1,1,0]
	v_pk_fma_f32 v[6:7], v[6:7], v[16:17], 0 op_sel_hi:[1,1,0]
	v_add_f32_e32 v3, 1.0, v3
	v_rcp_f32_e32 v18, v3
	v_mul_f32_e32 v3, 0xbfb8aa3b, v11
	v_exp_f32_e32 v3, v3
	v_pk_fma_f32 v[14:15], v[0:1], v[16:17], v[14:15]
	v_add_f32_e32 v3, 1.0, v3
	v_rcp_f32_e32 v19, v3
	s_nop 0
	v_pk_mul_f32 v[10:11], v[10:11], v[18:19]
	s_nop 0
	v_cvt_pk_bf16_f32 v3, v10, v11
	s_waitcnt vmcnt(18)
	v_lshlrev_b32_e32 v10, 16, v56
	v_and_b32_e32 v11, 0xffff0000, v56
	v_pk_fma_f32 v[12:13], v[4:5], v[10:11], v[12:13]
	v_pk_fma_f32 v[14:15], v[8:9], v[10:11], v[14:15]
	v_mul_f32_e32 v18, 0xbfb8aa3b, v12
	v_mul_f32_e32 v19, 0xbfb8aa3b, v13
	v_exp_f32_e32 v18, v18
	v_exp_f32_e32 v19, v19
	v_pk_fma_f32 v[0:1], v[0:1], v[10:11], v[6:7]
	v_add_f32_e32 v18, 1.0, v18
	v_add_f32_e32 v19, 1.0, v19
	v_rcp_f32_e32 v18, v18
	v_rcp_f32_e32 v19, v19
	s_nop 0
	v_pk_mul_f32 v[12:13], v[12:13], v[18:19]
	s_nop 0
	v_cvt_pk_bf16_f32 v12, v12, v13
	v_add_u32_e32 v13, 0x9a00, v2
	ds_write2_b32 v13, v3, v12 offset0:108 offset1:176
	s_waitcnt vmcnt(17)
	v_lshlrev_b32_e32 v12, 16, v55
	v_and_b32_e32 v13, 0xffff0000, v55
	v_pk_fma_f32 v[14:15], v[4:5], v[12:13], v[14:15]
	v_pk_fma_f32 v[0:1], v[8:9], v[12:13], v[0:1]
	v_mul_f32_e32 v3, 0xbfb8aa3b, v14
	v_exp_f32_e32 v3, v3
	s_nop 0
	v_add_f32_e32 v3, 1.0, v3
	v_rcp_f32_e32 v18, v3
	v_mul_f32_e32 v3, 0xbfb8aa3b, v15
	v_exp_f32_e32 v3, v3
	s_nop 0
	v_add_f32_e32 v3, 1.0, v3
	v_rcp_f32_e32 v19, v3
	s_nop 0
	v_pk_mul_f32 v[14:15], v[14:15], v[18:19]
	s_nop 0
	v_cvt_pk_bf16_f32 v3, v14, v15
	s_waitcnt vmcnt(16)
	v_lshlrev_b32_e32 v14, 16, v54
	v_and_b32_e32 v15, 0xffff0000, v54
	v_pk_fma_f32 v[0:1], v[4:5], v[14:15], v[0:1]
	s_nop 0
	v_mul_f32_e32 v4, 0xbfb8aa3b, v0
	v_mul_f32_e32 v5, 0xbfb8aa3b, v1
	v_exp_f32_e32 v4, v4
	v_exp_f32_e32 v5, v5
	v_add_f32_e32 v4, 1.0, v4
	v_add_f32_e32 v5, 1.0, v5
	v_rcp_f32_e32 v4, v4
	v_rcp_f32_e32 v5, v5
	s_nop 0
	v_pk_mul_f32 v[0:1], v[0:1], v[4:5]
	s_nop 0
	v_cvt_pk_bf16_f32 v0, v0, v1
	v_add_u32_e32 v1, 0x9c00, v2
	ds_write2_b32 v1, v3, v0 offset0:116 offset1:184
	s_add_i32 s8, 0, 0x1a000
	v_lshl_add_u32 v0, v50, 2, s8
	s_movk_i32 s0, 0x1040
	v_mad_u64_u32 v[2:3], s[6:7], v202, s0, v[0:1]
	s_movk_i32 s0, 0x104
	v_mad_u64_u32 v[0:1], s[6:7], v205, s0, v[0:1]
	v_add_u32_e32 v1, 0x400, v0
	s_waitcnt vmcnt(15)
	ds_write_b32 v2, v24
	s_waitcnt vmcnt(13)
	ds_write2_b32 v0, v20, v21 offset1:65
	s_waitcnt vmcnt(11)
	ds_write2_b32 v0, v22, v25 offset0:130 offset1:195
	s_waitcnt vmcnt(9)
	ds_write2_b32 v1, v23, v26 offset0:4 offset1:69
	s_waitcnt vmcnt(7)
	ds_write2_b32 v1, v27, v29 offset0:134 offset1:199
	v_add_u32_e32 v1, 0x800, v0
	s_waitcnt vmcnt(5)
	ds_write2_b32 v1, v28, v30 offset0:8 offset1:73
	s_waitcnt vmcnt(3)
	ds_write2_b32 v1, v31, v49 offset0:138 offset1:203
	v_add_u32_e32 v1, 0xc00, v0
	s_waitcnt vmcnt(1)
	ds_write2_b32 v1, v48, v52 offset0:12 offset1:77
	s_waitcnt vmcnt(0)
	ds_write_b32 v0, v53 offset:3640
	v_cmp_gt_i32_e32 vcc, s83, v64
	s_and_saveexec_b64 s[6:7], vcc
	s_cbranch_execz .LBB0_1325
	v_lshl_add_u32 v1, v64, 2, 0
	ds_write_b32 v1, v236 offset:1536
